# v10 + the gate/up epilogue keeps the 8 per-row mean-square values of the workgroup's token rows in registers across its tiles (same rows every round): ssq loads, reductions and their wait only on the
# speedup vs baseline: 1.0196x; 1.0049x over previous
; #define PG8_BAR __builtin_amdgcn_s_barrier()
; template <class Epi, class Sched, bool ALIGN_EPI = false, bool SP2 = false, bool F16 = false, bool TOKPERM = false>
; __device__ __forceinline__ void gemm_phase(PG8_LAS unsigned char* lds, const Gemm g, const Sched& S, const Epi& E, int wv) {
;     ...
;     const int tid = tid_, wid = __builtin_amdgcn_readfirstlane(tid >> 6), lane = tid & 63, wr = wid >> 2, wc = wid & 3, fr = lane & 15, fq = lane >> 4;
;     const int K = g.K, nt = K / BK;
;     unsigned voffA[2], voffB[2];
; #pragma unroll
;     for (int i = 0; i < 2; ++i) { int R, C; stage_rc(tid * 16 + i * 8192, R, C); const int Rb = Epi::PERM ? ((R & ~31) + perm32(R & 31)) : R;
;         const int Ra = TOKPERM ? ((R & ~63) + 4 * (R & 15) + ((R >> 4) & 3)) : R;
;         voffA[i] = (unsigned)(Ra * K + C) * 2u; voffB[i] = (unsigned)(Rb * K + C) * 2u; }
;     const size_t kstep = (size_t)(BK * 2);
;     const size_t hstep = (size_t)HALF * K * 2;
;     const size_t tstep = 2 * hstep;
;     const unsigned ldsw = (unsigned)wid * 1024u;
;     const int aoff = lds_byte(wr * 64 + fr, fq * 8), boff = lds_byte(wc * 32 + fr, fq * 8);
;     ...
;     Unit cur, nxt; int ui = 0;
;     if (!S.next(0, cur)) return;
;     f32x4 acc[2][2][4][2];
; #pragma unroll
;     for (int a = 0; a < 2; ++a)
; #pragma unroll
;         for (int b = 0; b < 2; ++b)
; #pragma unroll
;             for (int m = 0; m < 4; ++m)
; #pragma unroll
;                 for (int n = 0; n < 2; ++n) acc[a][b][m][n] = (f32x4){0.f, 0.f, 0.f, 0.f};
;     bf16x8 At[4][2], B0[2][2], B1[2][2];
;     const char* cA = (const char*)g.A + (size_t)cur.pm * tstep; const char* cB = (const char*)g.Bt + (size_t)cur.pn * tstep;
;     S.a_ready(cur);
;     if constexpr (SP2) {
;         PG8_STAGE(PG8_SB(0, 0), cB, voffB); PG8_STAGE(PG8_SB(0, 1), cB + hstep, voffB); PG8_STAGE(PG8_SA(0, 0), cA, voffA); PG8_STAGE(PG8_SA(0, 1), cA + hstep, voffA);
;         if (wr == 1) PG8_BAR;
;         PG8_WAIT_V(2); PG8_BAR;
;         PG8_STAGE(PG8_SB(1, 0), cB + kstep, voffB); PG8_STAGE(PG8_SA(1, 0), cA + kstep, voffA); PG8_STAGE(PG8_SB(1, 1), cB + hstep + kstep, voffB);
;         PG8_WAIT_V(6); PG8_BAR;
;     } else {
;         PG8_STAGE(PG8_SB(0, 0), cB, voffB); PG8_STAGE(PG8_SA(0, 0), cA, voffA); PG8_STAGE(PG8_SB(0, 1), cB + hstep, voffB); PG8_STAGE(PG8_SA(0, 1), cA + hstep, voffA);
;         if (wr == 1) PG8_BAR;
;         PG8_WAIT_V(4); PG8_BAR;
.LBB0_175:
	s_lshl_b32 s5, s16, 5
	s_add_i32 s64, s20, 0x18000
	s_mov_b64 s[16:17], 0x80
	s_and_b32 s22, s5, 0x60
	v_lshl_add_u64 v[6:7], v[6:7], 0, s[16:17]
	s_mov_b32 m0, s64
	s_add_i32 s65, s20, 0x1a000
	s_lshl_b32 s19, s18, 13
	s_lshl_b32 s44, s22, 7
	s_waitcnt vmcnt(2)
	s_barrier
	global_load_lds_dwordx4 v[6:7], off
	v_lshl_add_u64 v[4:5], v[4:5], 0, s[16:17]
	s_mov_b32 m0, s65
	s_add_i32 s66, s20, 0x8000
	s_add_i32 s68, s20, 0xa000
	global_load_lds_dwordx4 v[4:5], off
	v_lshl_add_u64 v[0:1], v[0:1], 0, s[16:17]
	s_mov_b32 m0, s66
	s_add_u32 s48, s8, 0x40080
	global_load_lds_dwordx4 v[0:1], off
	v_lshl_add_u64 v[0:1], v[2:3], 0, s[16:17]
	s_mov_b32 m0, s68
	s_addc_u32 s49, s9, 0
	s_add_i32 s69, s20, 0x1c000
	global_load_lds_dwordx4 v[0:1], off
	v_lshl_add_u64 v[0:1], s[48:49], 0, v[132:133]
	s_mov_b32 m0, s69
	s_add_i32 s70, s20, 0x1e000
	global_load_lds_dwordx4 v[0:1], off
	v_lshl_add_u64 v[0:1], s[48:49], 0, v[128:129]
	s_mov_b32 m0, s70
	v_lshlrev_b32_e32 v2, 2, v9
	global_load_lds_dwordx4 v[0:1], off
	v_bfe_u32 v1, v9, 4, 2
	v_and_b32_e32 v0, 15, v9
	v_lshlrev_b32_e32 v136, 4, v1
	v_lshl_or_b32 v154, v1, 3, s22
	v_lshlrev_b32_e32 v1, 14, v13
	v_lshl_or_b32 v151, s18, 6, v0
	v_lshl_or_b32 v0, v0, 6, v136
	v_and_b32_e32 v2, 32, v2
	v_and_b32_e32 v1, 0xffff8000, v1
	v_bitop3_b32 v153, v0, s19, v2 bitop3:0xde
	v_bitop3_b32 v0, v0, s44, v2 bitop3:0xde
	v_lshl_add_u32 v1, v12, 11, v1
	v_and_b32_e32 v2, 1, v13
	v_lshl_or_b32 v1, v2, 6, v1
	v_lshl_add_u32 v140, v14, 1, v1
	v_lshlrev_b32_e32 v1, 14, v8
	v_and_b32_e32 v1, 0xffff8000, v1
	s_waitcnt vmcnt(6)
	v_lshl_add_u32 v1, v10, 11, v1
	v_and_b32_e32 v2, 1, v8
	s_cmpk_lt_u32 s3, 0x100
	v_lshl_or_b32 v1, v2, 6, v1
	s_sext_i32_i16 s5, s2
	s_cselect_b64 s[18:19], -1, 0
	v_lshl_add_u64 v[138:139], s[42:43], 0, v[136:137]
	s_ashr_i32 s71, s28, 31
	s_mov_b32 s72, s28
	v_mov_b32_e32 v141, v137
	v_lshl_add_u32 v142, v11, 1, v1
	v_mov_b32_e32 v143, v137
	v_mov_b64_e32 v[144:145], 0x580
	v_mov_b64_e32 v[146:147], 0x57f
	v_or_b32_e32 v155, 0x10000, v0
	v_add_u32_e32 v156, 0x10400, v0
	v_add_u32_e32 v157, 0x10800, v0
	v_add_u32_e32 v158, 0x10c00, v0
	v_or_b32_e32 v159, 0x14000, v0
	v_add_u32_e32 v160, 0x14400, v0
	v_add_u32_e32 v161, 0x14800, v0
	v_add_u32_e32 v162, 0x14c00, v0
	s_add_i32 s73, s20, 0xc000
	s_add_i32 s74, s20, 0xe000
	v_or_b32_e32 v163, 0x18000, v0
	v_add_u32_e32 v164, 0x18400, v0
	v_add_u32_e32 v165, 0x18800, v0
	v_add_u32_e32 v166, 0x18c00, v0
	v_or_b32_e32 v167, 0x1c000, v0
	v_add_u32_e32 v168, 0x1c400, v0
	v_add_u32_e32 v169, 0x1c800, v0
	v_add_u32_e32 v170, 0x1cc00, v0
	v_mbcnt_hi_u32_b32 v171, -1, v226
	s_mov_b32 s22, 0x3a800000
	s_mov_b32 s44, 0x358637bd
	s_mov_b32 s75, 0x800000
	s_movk_i32 s76, 0xb00
	s_barrier
	s_mov_b32 s99, -1
	s_branch .LBB0_178

; __device__ __forceinline__ unsigned pk2(float lo, float hi) { f32x2_t v = {lo, hi}; bf16x2_t b = __builtin_convertvector(v, bf16x2_t); return __builtin_bit_cast(unsigned, b); }
; __device__ __forceinline__ float sigm(float x) { return frcp(1.f + fexp2(-LOG2E * x)); }
;   __device__ __forceinline__ void operator()(const pg8::f32x4 (&acc)[2][2][4][2], const pg8::Unit& u, int wr, int wc, int fr, int fq) const {
;     ...
;     const int row0 = u.pm * 256 + wr * 64 + fr + z, col0 = u.pn * 128 + wc * 32 + 8 * fq + z;
; #pragma unroll
;     for (int ai = 0; ai < 2; ++ai) {
;       float rs[4];
; #pragma unroll
;       for (int m = 0; m < 4; ++m) { const f32x4 a = *(const f32x4*)(ssq + (unsigned)(row0 + ai * 128 + m * 16) * 16 + 4 * fq); rs[m] = (a[0] + a[1]) + (a[2] + a[3]); }
; #pragma unroll
;       for (int m = 0; m < 4; ++m) { float v = rs[m]; v += __shfl_xor(v, 16); v += __shfl_xor(v, 32); rs[m] = rsqrtf(v * (1.f / 1024.f) + EPS); }
; #pragma unroll
;       for (int m = 0; m < 4; ++m) {
;         const float r = rs[m]; float v[8];
; #pragma unroll
;         for (int n = 0; n < 2; ++n)
; #pragma unroll
;           for (int c = 0; c < 4; ++c) { const float g = acc[ai][0][m][n][c] * r, uu = acc[ai][1][m][n][c] * r; v[4 * n + c] = g * sigm(g) * uu; }
;         u32x4 w; w.x = pk2(v[0], v[1]); w.y = pk2(v[2], v[3]); w.z = pk2(v[4], v[5]); w.w = pk2(v[6], v[7]);
.LBB0_184:
	s_lshl_b32 s4, s4, 8
	s_cmp_eq_u32 s4, s99
	s_mov_b32 s98, 0x3a800000
	s_mov_b32 s100, 0xb0000
	s_mov_b32 s101, 0
	v_add_u32_e32 v148, s4, v151
	v_lshl_or_b32 v152, s5, 7, v154
	v_mul_u32_u24_e32 v136, 0xb00, v148
	v_mov_b32_e32 v150, 0x358637bd
	v_add_u32_e32 v136, v136, v152
	v_lshl_add_u64 v[240:241], v[136:137], 1, s[38:39]
	s_cbranch_scc1 .Lgu_181_cached
	v_lshlrev_b32_e32 v136, 4, v148
	v_lshl_add_u64 v[242:243], v[136:137], 2, v[138:139]
	global_load_dwordx4 v[172:175], v[242:243], off
	global_load_dwordx4 v[176:179], v[242:243], off offset:1024
	global_load_dwordx4 v[180:183], v[242:243], off offset:2048
	global_load_dwordx4 v[184:187], v[242:243], off offset:3072
	v_add_u32_e32 v136, 0x800, v136
	v_lshl_add_u64 v[242:243], v[136:137], 2, v[138:139]
	global_load_dwordx4 v[188:191], v[242:243], off
	global_load_dwordx4 v[192:195], v[242:243], off offset:1024
	global_load_dwordx4 v[196:199], v[242:243], off offset:2048
	global_load_dwordx4 v[200:203], v[242:243], off offset:3072
	s_waitcnt vmcnt(0)
	v_add_f32_e32 v204, v172, v173
	v_add_f32_e32 v228, v174, v175
	v_add_f32_e32 v205, v176, v177
	v_add_f32_e32 v229, v178, v179
	v_add_f32_e32 v206, v180, v181
	v_add_f32_e32 v230, v182, v183
	v_add_f32_e32 v207, v184, v185
	v_add_f32_e32 v231, v186, v187
	v_add_f32_e32 v208, v188, v189
	v_add_f32_e32 v232, v190, v191
	v_add_f32_e32 v209, v192, v193
	v_add_f32_e32 v233, v194, v195
	v_add_f32_e32 v210, v196, v197
	v_add_f32_e32 v234, v198, v199
	v_add_f32_e32 v211, v200, v201
	v_add_f32_e32 v235, v202, v203
	v_add_f32_e32 v204, v204, v228
	v_add_f32_e32 v205, v205, v229
	v_add_f32_e32 v206, v206, v230
	v_add_f32_e32 v207, v207, v231
	v_add_f32_e32 v208, v208, v232
	v_add_f32_e32 v209, v209, v233
	v_add_f32_e32 v210, v210, v234
	v_add_f32_e32 v211, v211, v235
	v_mov_b32_e32 v228, v204
	v_mov_b32_e32 v229, v205
	v_mov_b32_e32 v230, v206
	v_mov_b32_e32 v231, v207
	v_mov_b32_e32 v232, v208
	v_mov_b32_e32 v233, v209
	v_mov_b32_e32 v234, v210
	v_mov_b32_e32 v235, v211
	v_permlane16_swap_b32_e32 v204, v228
	v_permlane16_swap_b32_e32 v205, v229
	v_permlane16_swap_b32_e32 v206, v230
	v_permlane16_swap_b32_e32 v207, v231
	v_permlane16_swap_b32_e32 v208, v232
	v_permlane16_swap_b32_e32 v209, v233
	v_permlane16_swap_b32_e32 v210, v234
	v_permlane16_swap_b32_e32 v211, v235
	v_add_f32_e32 v204, v204, v228
	v_add_f32_e32 v205, v205, v229
	v_add_f32_e32 v206, v206, v230
	v_add_f32_e32 v207, v207, v231
	v_add_f32_e32 v208, v208, v232
	v_add_f32_e32 v209, v209, v233
	v_add_f32_e32 v210, v210, v234
	v_add_f32_e32 v211, v211, v235
	v_mov_b32_e32 v228, v204
	v_mov_b32_e32 v229, v205
	v_mov_b32_e32 v230, v206
	v_mov_b32_e32 v231, v207
	v_mov_b32_e32 v232, v208
	v_mov_b32_e32 v233, v209
	v_mov_b32_e32 v234, v210
	v_mov_b32_e32 v235, v211
	v_permlane32_swap_b32_e32 v204, v228
	v_permlane32_swap_b32_e32 v205, v229
	v_permlane32_swap_b32_e32 v206, v230
	v_permlane32_swap_b32_e32 v207, v231
	v_permlane32_swap_b32_e32 v208, v232
	v_permlane32_swap_b32_e32 v209, v233
	v_permlane32_swap_b32_e32 v210, v234
	v_permlane32_swap_b32_e32 v211, v235
	v_add_f32_e32 v204, v204, v228
	v_add_f32_e32 v205, v205, v229
	v_add_f32_e32 v206, v206, v230
	v_add_f32_e32 v207, v207, v231
	v_add_f32_e32 v208, v208, v232
	v_add_f32_e32 v209, v209, v233
	v_add_f32_e32 v210, v210, v234
	v_add_f32_e32 v211, v211, v235
	v_fma_f32 v172, v204, s98, v150
	v_fma_f32 v174, v205, s98, v150
	v_fma_f32 v176, v206, s98, v150
	v_fma_f32 v178, v207, s98, v150
	v_fma_f32 v180, v208, s98, v150
	v_fma_f32 v182, v209, s98, v150
	v_fma_f32 v184, v210, s98, v150
	v_fma_f32 v186, v211, s98, v150
	v_mov_b32_e32 v246, v172
	v_mov_b32_e32 v247, v174
	v_mov_b32_e32 v248, v176
	v_mov_b32_e32 v249, v178
	v_mov_b32_e32 v250, v180
	v_mov_b32_e32 v251, v182
	v_mov_b32_e32 v253, v184
	v_mov_b32_e32 v254, v186
	s_mov_b32 s99, s4
	s_branch .Lgu_181_havew
.Lgu_181_cached:
	v_mov_b32_e32 v172, v246
	v_mov_b32_e32 v174, v247
	v_mov_b32_e32 v176, v248
	v_mov_b32_e32 v178, v249
	v_mov_b32_e32 v180, v250
	v_mov_b32_e32 v182, v251
	v_mov_b32_e32 v184, v253
	v_mov_b32_e32 v186, v254
.Lgu_181_havew:
	v_lshl_add_u64 v[242:243], v[240:241], 0, s[100:101]
	s_mov_b32 s100, 0x16000
	v_rsq_f32_e32 v188, v172
	v_rsq_f32_e32 v190, v174
	v_rsq_f32_e32 v192, v176
	v_rsq_f32_e32 v194, v178
	v_rsq_f32_e32 v196, v180
	v_rsq_f32_e32 v198, v182
	v_rsq_f32_e32 v200, v184
	v_rsq_f32_e32 v202, v186
	v_mul_f32_e32 v188, 0xbfb8aa3b, v188
	v_mul_f32_e32 v190, 0xbfb8aa3b, v190
	v_mul_f32_e32 v192, 0xbfb8aa3b, v192
	v_mul_f32_e32 v194, 0xbfb8aa3b, v194
	v_mul_f32_e32 v196, 0xbfb8aa3b, v196
	v_mul_f32_e32 v198, 0xbfb8aa3b, v198
	v_mul_f32_e32 v200, 0xbfb8aa3b, v200
	v_mul_f32_e32 v202, 0xbfb8aa3b, v202
	v_pk_mul_f32 v[228:229], v[124:125], v[188:189] op_sel_hi:[1,0]
	v_pk_mul_f32 v[230:231], v[126:127], v[188:189] op_sel_hi:[1,0]
	v_pk_mul_f32 v[232:233], v[116:117], v[188:189] op_sel_hi:[1,0]
	v_pk_mul_f32 v[234:235], v[118:119], v[188:189] op_sel_hi:[1,0]
	v_exp_f32_e32 v228, v228
	v_exp_f32_e32 v229, v229
	v_exp_f32_e32 v230, v230
	v_exp_f32_e32 v231, v231
	v_exp_f32_e32 v232, v232
	v_exp_f32_e32 v233, v233
	v_exp_f32_e32 v234, v234
	v_exp_f32_e32 v235, v235
	v_pk_mul_f32 v[124:125], v[124:125], v[120:121]
	v_pk_mul_f32 v[126:127], v[126:127], v[122:123]
	v_pk_mul_f32 v[116:117], v[116:117], v[112:113]
	v_pk_mul_f32 v[118:119], v[118:119], v[114:115]
	v_pk_fma_f32 v[228:229], v[228:229], v[172:173], v[172:173] op_sel_hi:[1,0,0]
	v_pk_fma_f32 v[230:231], v[230:231], v[172:173], v[172:173] op_sel_hi:[1,0,0]
	v_pk_fma_f32 v[232:233], v[232:233], v[172:173], v[172:173] op_sel_hi:[1,0,0]
	v_pk_fma_f32 v[234:235], v[234:235], v[172:173], v[172:173] op_sel_hi:[1,0,0]
; __device__ __forceinline__ unsigned pk2(float lo, float hi) { f32x2_t v = {lo, hi}; bf16x2_t b = __builtin_convertvector(v, bf16x2_t); return __builtin_bit_cast(unsigned, b); }
; __device__ __forceinline__ float sigm(float x) { return frcp(1.f + fexp2(-LOG2E * x)); }
;   __device__ __forceinline__ void operator()(const pg8::f32x4 (&acc)[2][2][4][2], const pg8::Unit& u, int wr, int wc, int fr, int fq) const {
;     ...
;       for (int m = 0; m < 4; ++m) {
;         const float r = rs[m]; float v[8];
; #pragma unroll
;         for (int n = 0; n < 2; ++n)
; #pragma unroll
;           for (int c = 0; c < 4; ++c) { const float g = acc[ai][0][m][n][c] * r, uu = acc[ai][1][m][n][c] * r; v[4 * n + c] = g * sigm(g) * uu; }
;         u32x4 w; w.x = pk2(v[0], v[1]); w.y = pk2(v[2], v[3]); w.z = pk2(v[4], v[5]); w.w = pk2(v[6], v[7]);
;         *(u32x4*)(hbuf + (unsigned)(row0 + ai * 128 + m * 16) * DFF + col0) = w;
	v_rcp_f32_e32 v228, v228
	v_rcp_f32_e32 v229, v229
	v_rcp_f32_e32 v230, v230
	v_rcp_f32_e32 v231, v231
	v_rcp_f32_e32 v232, v232
	v_rcp_f32_e32 v233, v233
	v_rcp_f32_e32 v234, v234
	v_rcp_f32_e32 v235, v235
	v_pk_mul_f32 v[124:125], v[124:125], v[228:229]
	v_pk_mul_f32 v[126:127], v[126:127], v[230:231]
	v_pk_mul_f32 v[116:117], v[116:117], v[232:233]
	v_pk_mul_f32 v[118:119], v[118:119], v[234:235]
	v_cvt_pk_bf16_f32 v236, v124, v125
	v_cvt_pk_bf16_f32 v237, v126, v127
	v_cvt_pk_bf16_f32 v238, v116, v117
	v_cvt_pk_bf16_f32 v239, v118, v119
	s_nop 0
	global_store_dwordx4 v[240:241], v[236:239], off
	v_lshl_add_u64 v[240:241], v[240:241], 0, s[100:101]
	v_pk_mul_f32 v[228:229], v[108:109], v[190:191] op_sel_hi:[1,0]
	v_pk_mul_f32 v[230:231], v[110:111], v[190:191] op_sel_hi:[1,0]
	v_pk_mul_f32 v[232:233], v[104:105], v[190:191] op_sel_hi:[1,0]
	v_pk_mul_f32 v[234:235], v[106:107], v[190:191] op_sel_hi:[1,0]
	v_exp_f32_e32 v228, v228
	v_exp_f32_e32 v229, v229
	v_exp_f32_e32 v230, v230
	v_exp_f32_e32 v231, v231
	v_exp_f32_e32 v232, v232
	v_exp_f32_e32 v233, v233
	v_exp_f32_e32 v234, v234
	v_exp_f32_e32 v235, v235
	v_pk_mul_f32 v[108:109], v[108:109], v[100:101]
	v_pk_mul_f32 v[110:111], v[110:111], v[102:103]
	v_pk_mul_f32 v[104:105], v[104:105], v[96:97]
	v_pk_mul_f32 v[106:107], v[106:107], v[98:99]
	v_pk_fma_f32 v[228:229], v[228:229], v[174:175], v[174:175] op_sel_hi:[1,0,0]
	v_pk_fma_f32 v[230:231], v[230:231], v[174:175], v[174:175] op_sel_hi:[1,0,0]
	v_pk_fma_f32 v[232:233], v[232:233], v[174:175], v[174:175] op_sel_hi:[1,0,0]
	v_pk_fma_f32 v[234:235], v[234:235], v[174:175], v[174:175] op_sel_hi:[1,0,0]
	v_rcp_f32_e32 v228, v228
	v_rcp_f32_e32 v229, v229
	v_rcp_f32_e32 v230, v230
	v_rcp_f32_e32 v231, v231
	v_rcp_f32_e32 v232, v232
	v_rcp_f32_e32 v233, v233
	v_rcp_f32_e32 v234, v234
	v_rcp_f32_e32 v235, v235
	v_pk_mul_f32 v[108:109], v[108:109], v[228:229]
	v_pk_mul_f32 v[110:111], v[110:111], v[230:231]
	v_pk_mul_f32 v[104:105], v[104:105], v[232:233]
	v_pk_mul_f32 v[106:107], v[106:107], v[234:235]
	v_cvt_pk_bf16_f32 v236, v108, v109
	v_cvt_pk_bf16_f32 v237, v110, v111
	v_cvt_pk_bf16_f32 v238, v104, v105
	v_cvt_pk_bf16_f32 v239, v106, v107
	s_nop 0
	global_store_dwordx4 v[240:241], v[236:239], off
	v_lshl_add_u64 v[240:241], v[240:241], 0, s[100:101]
	v_pk_mul_f32 v[228:229], v[92:93], v[192:193] op_sel_hi:[1,0]
	v_pk_mul_f32 v[230:231], v[94:95], v[192:193] op_sel_hi:[1,0]
	v_pk_mul_f32 v[232:233], v[88:89], v[192:193] op_sel_hi:[1,0]
	v_pk_mul_f32 v[234:235], v[90:91], v[192:193] op_sel_hi:[1,0]
	v_exp_f32_e32 v228, v228
	v_exp_f32_e32 v229, v229
	v_exp_f32_e32 v230, v230
	v_exp_f32_e32 v231, v231
	v_exp_f32_e32 v232, v232
	v_exp_f32_e32 v233, v233
	v_exp_f32_e32 v234, v234
	v_exp_f32_e32 v235, v235
	v_pk_mul_f32 v[92:93], v[92:93], v[84:85]
	v_pk_mul_f32 v[94:95], v[94:95], v[86:87]
	v_pk_mul_f32 v[88:89], v[88:89], v[80:81]
	v_pk_mul_f32 v[90:91], v[90:91], v[82:83]
	v_pk_fma_f32 v[228:229], v[228:229], v[176:177], v[176:177] op_sel_hi:[1,0,0]
	v_pk_fma_f32 v[230:231], v[230:231], v[176:177], v[176:177] op_sel_hi:[1,0,0]
	v_pk_fma_f32 v[232:233], v[232:233], v[176:177], v[176:177] op_sel_hi:[1,0,0]
	v_pk_fma_f32 v[234:235], v[234:235], v[176:177], v[176:177] op_sel_hi:[1,0,0]
	v_rcp_f32_e32 v228, v228
	v_rcp_f32_e32 v229, v229
	v_rcp_f32_e32 v230, v230
	v_rcp_f32_e32 v231, v231
	v_rcp_f32_e32 v232, v232
	v_rcp_f32_e32 v233, v233
	v_rcp_f32_e32 v234, v234
	v_rcp_f32_e32 v235, v235
	v_pk_mul_f32 v[92:93], v[92:93], v[228:229]
	v_pk_mul_f32 v[94:95], v[94:95], v[230:231]
	v_pk_mul_f32 v[88:89], v[88:89], v[232:233]
	v_pk_mul_f32 v[90:91], v[90:91], v[234:235]
	v_cvt_pk_bf16_f32 v236, v92, v93
	v_cvt_pk_bf16_f32 v237, v94, v95
	v_cvt_pk_bf16_f32 v238, v88, v89
	v_cvt_pk_bf16_f32 v239, v90, v91
	s_nop 0
	global_store_dwordx4 v[240:241], v[236:239], off
	v_lshl_add_u64 v[240:241], v[240:241], 0, s[100:101]
	v_pk_mul_f32 v[228:229], v[76:77], v[194:195] op_sel_hi:[1,0]
	v_pk_mul_f32 v[230:231], v[78:79], v[194:195] op_sel_hi:[1,0]
	v_pk_mul_f32 v[232:233], v[72:73], v[194:195] op_sel_hi:[1,0]
	v_pk_mul_f32 v[234:235], v[74:75], v[194:195] op_sel_hi:[1,0]
	v_exp_f32_e32 v228, v228
	v_exp_f32_e32 v229, v229
	v_exp_f32_e32 v230, v230
	v_exp_f32_e32 v231, v231
	v_exp_f32_e32 v232, v232
	v_exp_f32_e32 v233, v233
	v_exp_f32_e32 v234, v234
	v_exp_f32_e32 v235, v235
	v_pk_mul_f32 v[76:77], v[76:77], v[68:69]
	v_pk_mul_f32 v[78:79], v[78:79], v[70:71]
	v_pk_mul_f32 v[72:73], v[72:73], v[64:65]
	v_pk_mul_f32 v[74:75], v[74:75], v[66:67]
	v_pk_fma_f32 v[228:229], v[228:229], v[178:179], v[178:179] op_sel_hi:[1,0,0]
	v_pk_fma_f32 v[230:231], v[230:231], v[178:179], v[178:179] op_sel_hi:[1,0,0]
	v_pk_fma_f32 v[232:233], v[232:233], v[178:179], v[178:179] op_sel_hi:[1,0,0]
	v_pk_fma_f32 v[234:235], v[234:235], v[178:179], v[178:179] op_sel_hi:[1,0,0]
	v_rcp_f32_e32 v228, v228
	v_rcp_f32_e32 v229, v229
	v_rcp_f32_e32 v230, v230
	v_rcp_f32_e32 v231, v231
	v_rcp_f32_e32 v232, v232
	v_rcp_f32_e32 v233, v233
	v_rcp_f32_e32 v234, v234
	v_rcp_f32_e32 v235, v235
	v_pk_mul_f32 v[76:77], v[76:77], v[228:229]
	v_pk_mul_f32 v[78:79], v[78:79], v[230:231]
	v_pk_mul_f32 v[72:73], v[72:73], v[232:233]
	v_pk_mul_f32 v[74:75], v[74:75], v[234:235]
	v_cvt_pk_bf16_f32 v236, v76, v77
	v_cvt_pk_bf16_f32 v237, v78, v79
	v_cvt_pk_bf16_f32 v238, v72, v73
	v_cvt_pk_bf16_f32 v239, v74, v75
	s_nop 0
	global_store_dwordx4 v[240:241], v[236:239], off
	v_pk_mul_f32 v[228:229], v[60:61], v[196:197] op_sel_hi:[1,0]
	v_pk_mul_f32 v[230:231], v[62:63], v[196:197] op_sel_hi:[1,0]
	v_pk_mul_f32 v[232:233], v[56:57], v[196:197] op_sel_hi:[1,0]
	v_pk_mul_f32 v[234:235], v[58:59], v[196:197] op_sel_hi:[1,0]
; __device__ __forceinline__ unsigned pk2(float lo, float hi) { f32x2_t v = {lo, hi}; bf16x2_t b = __builtin_convertvector(v, bf16x2_t); return __builtin_bit_cast(unsigned, b); }
; __device__ __forceinline__ float sigm(float x) { return frcp(1.f + fexp2(-LOG2E * x)); }
;   __device__ __forceinline__ void operator()(const pg8::f32x4 (&acc)[2][2][4][2], const pg8::Unit& u, int wr, int wc, int fr, int fq) const {
;     ...
;       for (int m = 0; m < 4; ++m) {
;         const float r = rs[m]; float v[8];
; #pragma unroll
;         for (int n = 0; n < 2; ++n)
; #pragma unroll
;           for (int c = 0; c < 4; ++c) { const float g = acc[ai][0][m][n][c] * r, uu = acc[ai][1][m][n][c] * r; v[4 * n + c] = g * sigm(g) * uu; }
;         u32x4 w; w.x = pk2(v[0], v[1]); w.y = pk2(v[2], v[3]); w.z = pk2(v[4], v[5]); w.w = pk2(v[6], v[7]);
;         *(u32x4*)(hbuf + (unsigned)(row0 + ai * 128 + m * 16) * DFF + col0) = w;
	v_exp_f32_e32 v228, v228
	v_exp_f32_e32 v229, v229
	v_exp_f32_e32 v230, v230
	v_exp_f32_e32 v231, v231
	v_exp_f32_e32 v232, v232
	v_exp_f32_e32 v233, v233
	v_exp_f32_e32 v234, v234
	v_exp_f32_e32 v235, v235
	v_pk_mul_f32 v[60:61], v[60:61], v[52:53]
	v_pk_mul_f32 v[62:63], v[62:63], v[54:55]
	v_pk_mul_f32 v[56:57], v[56:57], v[48:49]
	v_pk_mul_f32 v[58:59], v[58:59], v[50:51]
	v_pk_fma_f32 v[228:229], v[228:229], v[180:181], v[180:181] op_sel_hi:[1,0,0]
	v_pk_fma_f32 v[230:231], v[230:231], v[180:181], v[180:181] op_sel_hi:[1,0,0]
	v_pk_fma_f32 v[232:233], v[232:233], v[180:181], v[180:181] op_sel_hi:[1,0,0]
	v_pk_fma_f32 v[234:235], v[234:235], v[180:181], v[180:181] op_sel_hi:[1,0,0]
	v_rcp_f32_e32 v228, v228
	v_rcp_f32_e32 v229, v229
	v_rcp_f32_e32 v230, v230
	v_rcp_f32_e32 v231, v231
	v_rcp_f32_e32 v232, v232
	v_rcp_f32_e32 v233, v233
	v_rcp_f32_e32 v234, v234
	v_rcp_f32_e32 v235, v235
	v_pk_mul_f32 v[60:61], v[60:61], v[228:229]
	v_pk_mul_f32 v[62:63], v[62:63], v[230:231]
	v_pk_mul_f32 v[56:57], v[56:57], v[232:233]
	v_pk_mul_f32 v[58:59], v[58:59], v[234:235]
	v_cvt_pk_bf16_f32 v236, v60, v61
	v_cvt_pk_bf16_f32 v237, v62, v63
	v_cvt_pk_bf16_f32 v238, v56, v57
	v_cvt_pk_bf16_f32 v239, v58, v59
	s_nop 0
	global_store_dwordx4 v[242:243], v[236:239], off
	v_lshl_add_u64 v[242:243], v[242:243], 0, s[100:101]
	v_pk_mul_f32 v[228:229], v[44:45], v[198:199] op_sel_hi:[1,0]
	v_pk_mul_f32 v[230:231], v[46:47], v[198:199] op_sel_hi:[1,0]
	v_pk_mul_f32 v[232:233], v[40:41], v[198:199] op_sel_hi:[1,0]
	v_pk_mul_f32 v[234:235], v[42:43], v[198:199] op_sel_hi:[1,0]
	v_exp_f32_e32 v228, v228
	v_exp_f32_e32 v229, v229
	v_exp_f32_e32 v230, v230
	v_exp_f32_e32 v231, v231
	v_exp_f32_e32 v232, v232
	v_exp_f32_e32 v233, v233
	v_exp_f32_e32 v234, v234
	v_exp_f32_e32 v235, v235
	v_pk_mul_f32 v[44:45], v[44:45], v[36:37]
	v_pk_mul_f32 v[46:47], v[46:47], v[38:39]
	v_pk_mul_f32 v[40:41], v[40:41], v[32:33]
	v_pk_mul_f32 v[42:43], v[42:43], v[34:35]
	v_pk_fma_f32 v[228:229], v[228:229], v[182:183], v[182:183] op_sel_hi:[1,0,0]
	v_pk_fma_f32 v[230:231], v[230:231], v[182:183], v[182:183] op_sel_hi:[1,0,0]
	v_pk_fma_f32 v[232:233], v[232:233], v[182:183], v[182:183] op_sel_hi:[1,0,0]
	v_pk_fma_f32 v[234:235], v[234:235], v[182:183], v[182:183] op_sel_hi:[1,0,0]
	v_rcp_f32_e32 v228, v228
	v_rcp_f32_e32 v229, v229
	v_rcp_f32_e32 v230, v230
	v_rcp_f32_e32 v231, v231
	v_rcp_f32_e32 v232, v232
	v_rcp_f32_e32 v233, v233
	v_rcp_f32_e32 v234, v234
	v_rcp_f32_e32 v235, v235
	v_pk_mul_f32 v[44:45], v[44:45], v[228:229]
	v_pk_mul_f32 v[46:47], v[46:47], v[230:231]
	v_pk_mul_f32 v[40:41], v[40:41], v[232:233]
	v_pk_mul_f32 v[42:43], v[42:43], v[234:235]
	v_cvt_pk_bf16_f32 v236, v44, v45
	v_cvt_pk_bf16_f32 v237, v46, v47
	v_cvt_pk_bf16_f32 v238, v40, v41
	v_cvt_pk_bf16_f32 v239, v42, v43
	s_nop 0
	global_store_dwordx4 v[242:243], v[236:239], off
	v_lshl_add_u64 v[242:243], v[242:243], 0, s[100:101]
	v_pk_mul_f32 v[228:229], v[28:29], v[200:201] op_sel_hi:[1,0]
	v_pk_mul_f32 v[230:231], v[30:31], v[200:201] op_sel_hi:[1,0]
	v_pk_mul_f32 v[232:233], v[24:25], v[200:201] op_sel_hi:[1,0]
	v_pk_mul_f32 v[234:235], v[26:27], v[200:201] op_sel_hi:[1,0]
	v_exp_f32_e32 v228, v228
	v_exp_f32_e32 v229, v229
	v_exp_f32_e32 v230, v230
	v_exp_f32_e32 v231, v231
	v_exp_f32_e32 v232, v232
	v_exp_f32_e32 v233, v233
	v_exp_f32_e32 v234, v234
	v_exp_f32_e32 v235, v235
	v_pk_mul_f32 v[28:29], v[28:29], v[20:21]
	v_pk_mul_f32 v[30:31], v[30:31], v[22:23]
	v_pk_mul_f32 v[24:25], v[24:25], v[16:17]
	v_pk_mul_f32 v[26:27], v[26:27], v[18:19]
	v_pk_fma_f32 v[228:229], v[228:229], v[184:185], v[184:185] op_sel_hi:[1,0,0]
	v_pk_fma_f32 v[230:231], v[230:231], v[184:185], v[184:185] op_sel_hi:[1,0,0]
	v_pk_fma_f32 v[232:233], v[232:233], v[184:185], v[184:185] op_sel_hi:[1,0,0]
	v_pk_fma_f32 v[234:235], v[234:235], v[184:185], v[184:185] op_sel_hi:[1,0,0]
	v_rcp_f32_e32 v228, v228
	v_rcp_f32_e32 v229, v229
	v_rcp_f32_e32 v230, v230
	v_rcp_f32_e32 v231, v231
	v_rcp_f32_e32 v232, v232
	v_rcp_f32_e32 v233, v233
	v_rcp_f32_e32 v234, v234
	v_rcp_f32_e32 v235, v235
	v_pk_mul_f32 v[28:29], v[28:29], v[228:229]
	v_pk_mul_f32 v[30:31], v[30:31], v[230:231]
	v_pk_mul_f32 v[24:25], v[24:25], v[232:233]
	v_pk_mul_f32 v[26:27], v[26:27], v[234:235]
	v_cvt_pk_bf16_f32 v236, v28, v29
	v_cvt_pk_bf16_f32 v237, v30, v31
	v_cvt_pk_bf16_f32 v238, v24, v25
	v_cvt_pk_bf16_f32 v239, v26, v27
	s_nop 0
	global_store_dwordx4 v[242:243], v[236:239], off
	v_lshl_add_u64 v[242:243], v[242:243], 0, s[100:101]
	v_pk_mul_f32 v[228:229], v[12:13], v[202:203] op_sel_hi:[1,0]
	v_pk_mul_f32 v[230:231], v[14:15], v[202:203] op_sel_hi:[1,0]
	v_pk_mul_f32 v[232:233], v[8:9], v[202:203] op_sel_hi:[1,0]
	v_pk_mul_f32 v[234:235], v[10:11], v[202:203] op_sel_hi:[1,0]
	v_exp_f32_e32 v228, v228
	v_exp_f32_e32 v229, v229
	v_exp_f32_e32 v230, v230
	v_exp_f32_e32 v231, v231
	v_exp_f32_e32 v232, v232
	v_exp_f32_e32 v233, v233
	v_exp_f32_e32 v234, v234
	v_exp_f32_e32 v235, v235
	v_pk_mul_f32 v[12:13], v[12:13], v[4:5]
	v_pk_mul_f32 v[14:15], v[14:15], v[6:7]
	v_pk_mul_f32 v[8:9], v[8:9], v[0:1]
	v_pk_mul_f32 v[10:11], v[10:11], v[2:3]
	v_pk_fma_f32 v[228:229], v[228:229], v[186:187], v[186:187] op_sel_hi:[1,0,0]
	v_pk_fma_f32 v[230:231], v[230:231], v[186:187], v[186:187] op_sel_hi:[1,0,0]
	v_pk_fma_f32 v[232:233], v[232:233], v[186:187], v[186:187] op_sel_hi:[1,0,0]
	v_pk_fma_f32 v[234:235], v[234:235], v[186:187], v[186:187] op_sel_hi:[1,0,0]
	v_rcp_f32_e32 v228, v228
	v_rcp_f32_e32 v229, v229
	v_rcp_f32_e32 v230, v230
	v_rcp_f32_e32 v231, v231
	v_rcp_f32_e32 v232, v232
	v_rcp_f32_e32 v233, v233
	v_rcp_f32_e32 v234, v234
	v_rcp_f32_e32 v235, v235
	v_pk_mul_f32 v[12:13], v[12:13], v[228:229]
	v_pk_mul_f32 v[14:15], v[14:15], v[230:231]
	v_pk_mul_f32 v[8:9], v[8:9], v[232:233]
	v_pk_mul_f32 v[10:11], v[10:11], v[234:235]
	v_cvt_pk_bf16_f32 v236, v12, v13
	v_cvt_pk_bf16_f32 v237, v14, v15
	v_cvt_pk_bf16_f32 v238, v8, v9
	v_cvt_pk_bf16_f32 v239, v10, v11
	s_nop 0
	global_store_dwordx4 v[242:243], v[236:239], off
	s_andn2_b64 vcc, exec, s[2:3]
	s_mov_b64 s[2:3], -1
	s_cbranch_vccnz .LBB0_177
	s_andn2_b64 vcc, exec, s[10:11]
	s_cbranch_vccnz .LBB0_176
	s_barrier
	s_branch .LBB0_176

; template <class Epi, class Sched, bool ALIGN_EPI = false, bool SP2 = false, bool F16 = false, bool TOKPERM = false>
; __device__ __forceinline__ void gemm_phase(PG8_LAS unsigned char* lds, const Gemm g, const Sched& S, const Epi& E, int wv) {
;     int tid_ = wv * 64 + lane_id(); asm volatile("" : "+v"(tid_));
;     const int tid = tid_, wid = __builtin_amdgcn_readfirstlane(tid >> 6), lane = tid & 63, wr = wid >> 2, wc = wid & 3, fr = lane & 15, fq = lane >> 4;
;     const int K = g.K, nt = K / BK;
;     unsigned voffA[2], voffB[2];
; #pragma unroll
;     for (int i = 0; i < 2; ++i) { int R, C; stage_rc(tid * 16 + i * 8192, R, C); const int Rb = Epi::PERM ? ((R & ~31) + perm32(R & 31)) : R;
;         const int Ra = TOKPERM ? ((R & ~63) + 4 * (R & 15) + ((R >> 4) & 3)) : R;
;         voffA[i] = (unsigned)(Ra * K + C) * 2u; voffB[i] = (unsigned)(Rb * K + C) * 2u; }
;     const size_t kstep = (size_t)(BK * 2);
;     const size_t hstep = (size_t)HALF * K * 2;
;     const size_t tstep = 2 * hstep;
;     const unsigned ldsw = (unsigned)wid * 1024u;
;     const int aoff = lds_byte(wr * 64 + fr, fq * 8), boff = lds_byte(wc * 32 + fr, fq * 8);
;     ...
;     Unit cur, nxt; int ui = 0;
;     if (!S.next(0, cur)) return;
;     f32x4 acc[2][2][4][2];
; #pragma unroll
;     for (int a = 0; a < 2; ++a)
; #pragma unroll
;         for (int b = 0; b < 2; ++b)
; #pragma unroll
;             for (int m = 0; m < 4; ++m)
; #pragma unroll
;                 for (int n = 0; n < 2; ++n) acc[a][b][m][n] = (f32x4){0.f, 0.f, 0.f, 0.f};
;     bf16x8 At[4][2], B0[2][2], B1[2][2];
;     const char* cA = (const char*)g.A + (size_t)cur.pm * tstep; const char* cB = (const char*)g.Bt + (size_t)cur.pn * tstep;
;     S.a_ready(cur);
;     if constexpr (SP2) {
;         PG8_STAGE(PG8_SB(0, 0), cB, voffB); PG8_STAGE(PG8_SB(0, 1), cB + hstep, voffB); PG8_STAGE(PG8_SA(0, 0), cA, voffA); PG8_STAGE(PG8_SA(0, 1), cA + hstep, voffA);
;         if (wr == 1) PG8_BAR;
;         PG8_WAIT_V(2); PG8_BAR;
;         PG8_STAGE(PG8_SB(1, 0), cB + kstep, voffB); PG8_STAGE(PG8_SA(1, 0), cA + kstep, voffA); PG8_STAGE(PG8_SB(1, 1), cB + hstep + kstep, voffB);
;         PG8_WAIT_V(6); PG8_BAR;
;     } else {
;         PG8_STAGE(PG8_SB(0, 0), cB, voffB); PG8_STAGE(PG8_SA(0, 0), cA, voffA); PG8_STAGE(PG8_SB(0, 1), cB + hstep, voffB); PG8_STAGE(PG8_SA(0, 1), cA + hstep, voffA);
;         if (wr == 1) PG8_BAR;
.LBB0_762:
	s_lshl_b32 s9, s16, 5
	s_add_i32 s45, s2, 0x18000
	s_mov_b64 s[16:17], 0x80
	s_and_b32 s20, s9, 0x60
	v_lshl_add_u64 v[6:7], v[6:7], 0, s[16:17]
	s_mov_b32 m0, s45
	s_add_i32 s49, s2, 0x1a000
	s_lshl_b32 s19, s18, 13
	s_lshl_b32 s48, s20, 7
	s_waitcnt vmcnt(2)
	s_barrier
	global_load_lds_dwordx4 v[6:7], off
	v_lshl_add_u64 v[4:5], v[4:5], 0, s[16:17]
	s_mov_b32 m0, s49
	s_add_i32 s60, s2, 0x8000
	s_add_i32 s61, s2, 0xa000
	global_load_lds_dwordx4 v[4:5], off
	v_lshl_add_u64 v[0:1], v[0:1], 0, s[16:17]
	s_mov_b32 m0, s60
	s_add_u32 s50, s12, 0x40080
	global_load_lds_dwordx4 v[0:1], off
	v_lshl_add_u64 v[0:1], v[2:3], 0, s[16:17]
	s_mov_b32 m0, s61
	s_addc_u32 s51, s13, 0
	s_add_i32 s62, s2, 0x1c000
	global_load_lds_dwordx4 v[0:1], off
	v_lshl_add_u64 v[0:1], s[50:51], 0, v[132:133]
	s_mov_b32 m0, s62
	s_add_i32 s63, s2, 0x1e000
	global_load_lds_dwordx4 v[0:1], off
	v_lshl_add_u64 v[0:1], s[50:51], 0, v[128:129]
	s_mov_b32 m0, s63
	v_lshlrev_b32_e32 v2, 2, v9
	global_load_lds_dwordx4 v[0:1], off
	v_bfe_u32 v1, v9, 4, 2
	v_and_b32_e32 v0, 15, v9
	v_lshlrev_b32_e32 v136, 4, v1
	v_lshl_or_b32 v154, v1, 3, s20
	v_lshlrev_b32_e32 v1, 14, v13
	v_lshl_or_b32 v151, s18, 6, v0
	v_lshl_or_b32 v0, v0, 6, v136
	v_and_b32_e32 v2, 32, v2
	v_and_b32_e32 v1, 0xffff8000, v1
	v_bitop3_b32 v153, v0, s19, v2 bitop3:0xde
	v_bitop3_b32 v0, v0, s48, v2 bitop3:0xde
	v_lshl_add_u32 v1, v12, 11, v1
	v_and_b32_e32 v2, 1, v13
	v_lshl_or_b32 v1, v2, 6, v1
	v_lshl_add_u32 v140, v14, 1, v1
	v_lshlrev_b32_e32 v1, 14, v8
	v_and_b32_e32 v1, 0xffff8000, v1
	s_waitcnt vmcnt(6)
	v_lshl_add_u32 v1, v10, 11, v1
	v_and_b32_e32 v2, 1, v8
	s_cmpk_lt_u32 s7, 0x100
	v_lshl_or_b32 v1, v2, 6, v1
	s_sext_i32_i16 s9, s6
	s_cselect_b64 s[18:19], -1, 0
	v_lshl_add_u64 v[138:139], s[42:43], 0, v[136:137]
	s_ashr_i32 s64, s28, 31
	s_mov_b32 s65, s28
	v_mov_b32_e32 v141, v137
	v_lshl_add_u32 v142, v11, 1, v1
	v_mov_b32_e32 v143, v137
	v_mov_b64_e32 v[144:145], 0x580
	v_mov_b64_e32 v[146:147], 0x57f
	v_or_b32_e32 v155, 0x10000, v0
	v_add_u32_e32 v156, 0x10400, v0
	v_add_u32_e32 v157, 0x10800, v0
	v_add_u32_e32 v158, 0x10c00, v0
	v_or_b32_e32 v159, 0x14000, v0
	v_add_u32_e32 v160, 0x14400, v0
	v_add_u32_e32 v161, 0x14800, v0
	v_add_u32_e32 v162, 0x14c00, v0
	s_add_i32 s66, s2, 0xc000
	s_add_i32 s67, s2, 0xe000
	v_or_b32_e32 v163, 0x18000, v0
	v_add_u32_e32 v164, 0x18400, v0
	v_add_u32_e32 v165, 0x18800, v0
	v_add_u32_e32 v166, 0x18c00, v0
	v_or_b32_e32 v167, 0x1c000, v0
	v_add_u32_e32 v168, 0x1c400, v0
	v_add_u32_e32 v169, 0x1c800, v0
	v_add_u32_e32 v170, 0x1cc00, v0
	v_mbcnt_hi_u32_b32 v171, -1, v226
	s_mov_b32 s20, 0x3a800000
	s_mov_b32 s48, 0x358637bd
	s_mov_b32 s68, 0x800000
	s_movk_i32 s69, 0xb00
	s_barrier
	s_mov_b32 s99, -1
	s_branch .LBB0_765

;   __device__ __forceinline__ void operator()(const pg8::f32x4 (&acc)[2][2][4][2], const pg8::Unit& u, int wr, int wc, int fr, int fq) const {
;     ...
;     const int row0 = u.pm * 256 + wr * 64 + fr + z, col0 = u.pn * 128 + wc * 32 + 8 * fq + z;
; #pragma unroll
;     for (int ai = 0; ai < 2; ++ai) {
;       float rs[4];
; #pragma unroll
;       for (int m = 0; m < 4; ++m) { const f32x4 a = *(const f32x4*)(ssq + (unsigned)(row0 + ai * 128 + m * 16) * 16 + 4 * fq); rs[m] = (a[0] + a[1]) + (a[2] + a[3]); }
; #pragma unroll
;       for (int m = 0; m < 4; ++m) { float v = rs[m]; v += __shfl_xor(v, 16); v += __shfl_xor(v, 32); rs[m] = rsqrtf(v * (1.f / 1024.f) + EPS); }
.LBB0_771:
	s_lshl_b32 s8, s8, 8
	s_cmp_eq_u32 s8, s99
	s_mov_b32 s98, 0x3a800000
	s_mov_b32 s100, 0xb0000
	s_mov_b32 s101, 0
	v_add_u32_e32 v148, s8, v151
	v_lshl_or_b32 v152, s9, 7, v154
	v_mul_u32_u24_e32 v136, 0xb00, v148
	v_mov_b32_e32 v150, 0x358637bd
	v_add_u32_e32 v136, v136, v152
	v_lshl_add_u64 v[240:241], v[136:137], 1, s[38:39]
	s_cbranch_scc1 .Lgu_768_cached
	v_lshlrev_b32_e32 v136, 4, v148
	v_lshl_add_u64 v[242:243], v[136:137], 2, v[138:139]
	global_load_dwordx4 v[172:175], v[242:243], off
	global_load_dwordx4 v[176:179], v[242:243], off offset:1024
	global_load_dwordx4 v[180:183], v[242:243], off offset:2048
	global_load_dwordx4 v[184:187], v[242:243], off offset:3072
	v_add_u32_e32 v136, 0x800, v136
	v_lshl_add_u64 v[242:243], v[136:137], 2, v[138:139]
	global_load_dwordx4 v[188:191], v[242:243], off
	global_load_dwordx4 v[192:195], v[242:243], off offset:1024
	global_load_dwordx4 v[196:199], v[242:243], off offset:2048
	global_load_dwordx4 v[200:203], v[242:243], off offset:3072
	s_waitcnt vmcnt(0)
	v_add_f32_e32 v204, v172, v173
	v_add_f32_e32 v228, v174, v175
	v_add_f32_e32 v205, v176, v177
	v_add_f32_e32 v229, v178, v179
	v_add_f32_e32 v206, v180, v181
	v_add_f32_e32 v230, v182, v183
	v_add_f32_e32 v207, v184, v185
	v_add_f32_e32 v231, v186, v187
	v_add_f32_e32 v208, v188, v189
	v_add_f32_e32 v232, v190, v191
	v_add_f32_e32 v209, v192, v193
	v_add_f32_e32 v233, v194, v195
	v_add_f32_e32 v210, v196, v197
	v_add_f32_e32 v234, v198, v199
	v_add_f32_e32 v211, v200, v201
	v_add_f32_e32 v235, v202, v203
	v_add_f32_e32 v204, v204, v228
	v_add_f32_e32 v205, v205, v229
	v_add_f32_e32 v206, v206, v230
	v_add_f32_e32 v207, v207, v231
	v_add_f32_e32 v208, v208, v232
	v_add_f32_e32 v209, v209, v233
	v_add_f32_e32 v210, v210, v234
	v_add_f32_e32 v211, v211, v235
	v_mov_b32_e32 v228, v204
	v_mov_b32_e32 v229, v205
	v_mov_b32_e32 v230, v206
	v_mov_b32_e32 v231, v207
	v_mov_b32_e32 v232, v208
	v_mov_b32_e32 v233, v209
	v_mov_b32_e32 v234, v210
	v_mov_b32_e32 v235, v211
	v_permlane16_swap_b32_e32 v204, v228
	v_permlane16_swap_b32_e32 v205, v229
	v_permlane16_swap_b32_e32 v206, v230
	v_permlane16_swap_b32_e32 v207, v231
	v_permlane16_swap_b32_e32 v208, v232
	v_permlane16_swap_b32_e32 v209, v233
	v_permlane16_swap_b32_e32 v210, v234
	v_permlane16_swap_b32_e32 v211, v235
	v_add_f32_e32 v204, v204, v228
	v_add_f32_e32 v205, v205, v229
	v_add_f32_e32 v206, v206, v230
	v_add_f32_e32 v207, v207, v231
	v_add_f32_e32 v208, v208, v232
	v_add_f32_e32 v209, v209, v233
	v_add_f32_e32 v210, v210, v234
	v_add_f32_e32 v211, v211, v235
	v_mov_b32_e32 v228, v204
	v_mov_b32_e32 v229, v205
	v_mov_b32_e32 v230, v206
	v_mov_b32_e32 v231, v207
	v_mov_b32_e32 v232, v208
	v_mov_b32_e32 v233, v209
	v_mov_b32_e32 v234, v210
	v_mov_b32_e32 v235, v211
	v_permlane32_swap_b32_e32 v204, v228
	v_permlane32_swap_b32_e32 v205, v229
	v_permlane32_swap_b32_e32 v206, v230
	v_permlane32_swap_b32_e32 v207, v231
	v_permlane32_swap_b32_e32 v208, v232
	v_permlane32_swap_b32_e32 v209, v233
	v_permlane32_swap_b32_e32 v210, v234
	v_permlane32_swap_b32_e32 v211, v235
	v_add_f32_e32 v204, v204, v228
	v_add_f32_e32 v205, v205, v229
	v_add_f32_e32 v206, v206, v230
	v_add_f32_e32 v207, v207, v231
	v_add_f32_e32 v208, v208, v232
	v_add_f32_e32 v209, v209, v233
	v_add_f32_e32 v210, v210, v234
	v_add_f32_e32 v211, v211, v235
	v_fma_f32 v172, v204, s98, v150
	v_fma_f32 v174, v205, s98, v150
	v_fma_f32 v176, v206, s98, v150
	v_fma_f32 v178, v207, s98, v150
	v_fma_f32 v180, v208, s98, v150
	v_fma_f32 v182, v209, s98, v150
	v_fma_f32 v184, v210, s98, v150
	v_fma_f32 v186, v211, s98, v150
	v_mov_b32_e32 v246, v172
	v_mov_b32_e32 v247, v174
	v_mov_b32_e32 v248, v176
	v_mov_b32_e32 v249, v178
	v_mov_b32_e32 v250, v180
	v_mov_b32_e32 v251, v182
	v_mov_b32_e32 v253, v184
	v_mov_b32_e32 v254, v186
	s_mov_b32 s99, s8
	s_branch .Lgu_768_havew

; __device__ __forceinline__ unsigned pk2(float lo, float hi) { f32x2_t v = {lo, hi}; bf16x2_t b = __builtin_convertvector(v, bf16x2_t); return __builtin_bit_cast(unsigned, b); }
; __device__ __forceinline__ float sigm(float x) { return frcp(1.f + fexp2(-LOG2E * x)); }
;   __device__ __forceinline__ void operator()(const pg8::f32x4 (&acc)[2][2][4][2], const pg8::Unit& u, int wr, int wc, int fr, int fq) const {
;     ...
;       for (int m = 0; m < 4; ++m) { float v = rs[m]; v += __shfl_xor(v, 16); v += __shfl_xor(v, 32); rs[m] = rsqrtf(v * (1.f / 1024.f) + EPS); }
; #pragma unroll
;       for (int m = 0; m < 4; ++m) {
;         const float r = rs[m]; float v[8];
; #pragma unroll
;         for (int n = 0; n < 2; ++n)
; #pragma unroll
;           for (int c = 0; c < 4; ++c) { const float g = acc[ai][0][m][n][c] * r, uu = acc[ai][1][m][n][c] * r; v[4 * n + c] = g * sigm(g) * uu; }
;         u32x4 w; w.x = pk2(v[0], v[1]); w.y = pk2(v[2], v[3]); w.z = pk2(v[4], v[5]); w.w = pk2(v[6], v[7]);
;         *(u32x4*)(hbuf + (unsigned)(row0 + ai * 128 + m * 16) * DFF + col0) = w;
.Lgu_768_havew:
	v_lshl_add_u64 v[242:243], v[240:241], 0, s[100:101]
	s_mov_b32 s100, 0x16000
	v_rsq_f32_e32 v188, v172
	v_rsq_f32_e32 v190, v174
	v_rsq_f32_e32 v192, v176
	v_rsq_f32_e32 v194, v178
	v_rsq_f32_e32 v196, v180
	v_rsq_f32_e32 v198, v182
	v_rsq_f32_e32 v200, v184
	v_rsq_f32_e32 v202, v186
	v_mul_f32_e32 v188, 0xbfb8aa3b, v188
	v_mul_f32_e32 v190, 0xbfb8aa3b, v190
	v_mul_f32_e32 v192, 0xbfb8aa3b, v192
	v_mul_f32_e32 v194, 0xbfb8aa3b, v194
	v_mul_f32_e32 v196, 0xbfb8aa3b, v196
	v_mul_f32_e32 v198, 0xbfb8aa3b, v198
	v_mul_f32_e32 v200, 0xbfb8aa3b, v200
	v_mul_f32_e32 v202, 0xbfb8aa3b, v202
	v_pk_mul_f32 v[228:229], v[124:125], v[188:189] op_sel_hi:[1,0]
	v_pk_mul_f32 v[230:231], v[126:127], v[188:189] op_sel_hi:[1,0]
	v_pk_mul_f32 v[232:233], v[116:117], v[188:189] op_sel_hi:[1,0]
	v_pk_mul_f32 v[234:235], v[118:119], v[188:189] op_sel_hi:[1,0]
	v_exp_f32_e32 v228, v228
	v_exp_f32_e32 v229, v229
	v_exp_f32_e32 v230, v230
	v_exp_f32_e32 v231, v231
	v_exp_f32_e32 v232, v232
	v_exp_f32_e32 v233, v233
	v_exp_f32_e32 v234, v234
	v_exp_f32_e32 v235, v235
	v_pk_mul_f32 v[124:125], v[124:125], v[120:121]
	v_pk_mul_f32 v[126:127], v[126:127], v[122:123]
	v_pk_mul_f32 v[116:117], v[116:117], v[112:113]
	v_pk_mul_f32 v[118:119], v[118:119], v[114:115]
	v_pk_fma_f32 v[228:229], v[228:229], v[172:173], v[172:173] op_sel_hi:[1,0,0]
	v_pk_fma_f32 v[230:231], v[230:231], v[172:173], v[172:173] op_sel_hi:[1,0,0]
	v_pk_fma_f32 v[232:233], v[232:233], v[172:173], v[172:173] op_sel_hi:[1,0,0]
	v_pk_fma_f32 v[234:235], v[234:235], v[172:173], v[172:173] op_sel_hi:[1,0,0]
	v_rcp_f32_e32 v228, v228
	v_rcp_f32_e32 v229, v229
	v_rcp_f32_e32 v230, v230
	v_rcp_f32_e32 v231, v231
	v_rcp_f32_e32 v232, v232
	v_rcp_f32_e32 v233, v233
	v_rcp_f32_e32 v234, v234
	v_rcp_f32_e32 v235, v235
	v_pk_mul_f32 v[124:125], v[124:125], v[228:229]
	v_pk_mul_f32 v[126:127], v[126:127], v[230:231]
	v_pk_mul_f32 v[116:117], v[116:117], v[232:233]
	v_pk_mul_f32 v[118:119], v[118:119], v[234:235]
	v_cvt_pk_bf16_f32 v236, v124, v125
	v_cvt_pk_bf16_f32 v237, v126, v127
	v_cvt_pk_bf16_f32 v238, v116, v117
	v_cvt_pk_bf16_f32 v239, v118, v119
	s_nop 0
	global_store_dwordx4 v[240:241], v[236:239], off
	v_lshl_add_u64 v[240:241], v[240:241], 0, s[100:101]
	v_pk_mul_f32 v[228:229], v[108:109], v[190:191] op_sel_hi:[1,0]
	v_pk_mul_f32 v[230:231], v[110:111], v[190:191] op_sel_hi:[1,0]
	v_pk_mul_f32 v[232:233], v[104:105], v[190:191] op_sel_hi:[1,0]
	v_pk_mul_f32 v[234:235], v[106:107], v[190:191] op_sel_hi:[1,0]
	v_exp_f32_e32 v228, v228
	v_exp_f32_e32 v229, v229
	v_exp_f32_e32 v230, v230
	v_exp_f32_e32 v231, v231
	v_exp_f32_e32 v232, v232
	v_exp_f32_e32 v233, v233
	v_exp_f32_e32 v234, v234
	v_exp_f32_e32 v235, v235
	v_pk_mul_f32 v[108:109], v[108:109], v[100:101]
	v_pk_mul_f32 v[110:111], v[110:111], v[102:103]
	v_pk_mul_f32 v[104:105], v[104:105], v[96:97]
	v_pk_mul_f32 v[106:107], v[106:107], v[98:99]
	v_pk_fma_f32 v[228:229], v[228:229], v[174:175], v[174:175] op_sel_hi:[1,0,0]
	v_pk_fma_f32 v[230:231], v[230:231], v[174:175], v[174:175] op_sel_hi:[1,0,0]
	v_pk_fma_f32 v[232:233], v[232:233], v[174:175], v[174:175] op_sel_hi:[1,0,0]
	v_pk_fma_f32 v[234:235], v[234:235], v[174:175], v[174:175] op_sel_hi:[1,0,0]
	v_rcp_f32_e32 v228, v228
	v_rcp_f32_e32 v229, v229
	v_rcp_f32_e32 v230, v230
	v_rcp_f32_e32 v231, v231
	v_rcp_f32_e32 v232, v232
	v_rcp_f32_e32 v233, v233
	v_rcp_f32_e32 v234, v234
	v_rcp_f32_e32 v235, v235
	v_pk_mul_f32 v[108:109], v[108:109], v[228:229]
	v_pk_mul_f32 v[110:111], v[110:111], v[230:231]
	v_pk_mul_f32 v[104:105], v[104:105], v[232:233]
	v_pk_mul_f32 v[106:107], v[106:107], v[234:235]
	v_cvt_pk_bf16_f32 v236, v108, v109
	v_cvt_pk_bf16_f32 v237, v110, v111
	v_cvt_pk_bf16_f32 v238, v104, v105
	v_cvt_pk_bf16_f32 v239, v106, v107
	s_nop 0
	global_store_dwordx4 v[240:241], v[236:239], off
	v_lshl_add_u64 v[240:241], v[240:241], 0, s[100:101]
	v_pk_mul_f32 v[228:229], v[92:93], v[192:193] op_sel_hi:[1,0]
	v_pk_mul_f32 v[230:231], v[94:95], v[192:193] op_sel_hi:[1,0]
	v_pk_mul_f32 v[232:233], v[88:89], v[192:193] op_sel_hi:[1,0]
	v_pk_mul_f32 v[234:235], v[90:91], v[192:193] op_sel_hi:[1,0]
	v_exp_f32_e32 v228, v228
	v_exp_f32_e32 v229, v229
	v_exp_f32_e32 v230, v230
	v_exp_f32_e32 v231, v231
	v_exp_f32_e32 v232, v232
	v_exp_f32_e32 v233, v233
	v_exp_f32_e32 v234, v234
	v_exp_f32_e32 v235, v235
	v_pk_mul_f32 v[92:93], v[92:93], v[84:85]
	v_pk_mul_f32 v[94:95], v[94:95], v[86:87]
	v_pk_mul_f32 v[88:89], v[88:89], v[80:81]
	v_pk_mul_f32 v[90:91], v[90:91], v[82:83]
	v_pk_fma_f32 v[228:229], v[228:229], v[176:177], v[176:177] op_sel_hi:[1,0,0]
	v_pk_fma_f32 v[230:231], v[230:231], v[176:177], v[176:177] op_sel_hi:[1,0,0]
	v_pk_fma_f32 v[232:233], v[232:233], v[176:177], v[176:177] op_sel_hi:[1,0,0]
	v_pk_fma_f32 v[234:235], v[234:235], v[176:177], v[176:177] op_sel_hi:[1,0,0]
	v_rcp_f32_e32 v228, v228
	v_rcp_f32_e32 v229, v229
	v_rcp_f32_e32 v230, v230
	v_rcp_f32_e32 v231, v231
	v_rcp_f32_e32 v232, v232
	v_rcp_f32_e32 v233, v233
	v_rcp_f32_e32 v234, v234
	v_rcp_f32_e32 v235, v235
	v_pk_mul_f32 v[92:93], v[92:93], v[228:229]
	v_pk_mul_f32 v[94:95], v[94:95], v[230:231]
	v_pk_mul_f32 v[88:89], v[88:89], v[232:233]
	v_pk_mul_f32 v[90:91], v[90:91], v[234:235]
	v_cvt_pk_bf16_f32 v236, v92, v93
	v_cvt_pk_bf16_f32 v237, v94, v95
	v_cvt_pk_bf16_f32 v238, v88, v89
	v_cvt_pk_bf16_f32 v239, v90, v91
	s_nop 0
	global_store_dwordx4 v[240:241], v[236:239], off
	v_lshl_add_u64 v[240:241], v[240:241], 0, s[100:101]
	v_pk_mul_f32 v[228:229], v[76:77], v[194:195] op_sel_hi:[1,0]
	v_pk_mul_f32 v[230:231], v[78:79], v[194:195] op_sel_hi:[1,0]
	v_pk_mul_f32 v[232:233], v[72:73], v[194:195] op_sel_hi:[1,0]
; __device__ __forceinline__ unsigned pk2(float lo, float hi) { f32x2_t v = {lo, hi}; bf16x2_t b = __builtin_convertvector(v, bf16x2_t); return __builtin_bit_cast(unsigned, b); }
; __device__ __forceinline__ float sigm(float x) { return frcp(1.f + fexp2(-LOG2E * x)); }
;   __device__ __forceinline__ void operator()(const pg8::f32x4 (&acc)[2][2][4][2], const pg8::Unit& u, int wr, int wc, int fr, int fq) const {
;     ...
;       for (int m = 0; m < 4; ++m) {
;         const float r = rs[m]; float v[8];
; #pragma unroll
;         for (int n = 0; n < 2; ++n)
; #pragma unroll
;           for (int c = 0; c < 4; ++c) { const float g = acc[ai][0][m][n][c] * r, uu = acc[ai][1][m][n][c] * r; v[4 * n + c] = g * sigm(g) * uu; }
;         u32x4 w; w.x = pk2(v[0], v[1]); w.y = pk2(v[2], v[3]); w.z = pk2(v[4], v[5]); w.w = pk2(v[6], v[7]);
;         *(u32x4*)(hbuf + (unsigned)(row0 + ai * 128 + m * 16) * DFF + col0) = w;
	v_pk_mul_f32 v[234:235], v[74:75], v[194:195] op_sel_hi:[1,0]
	v_exp_f32_e32 v228, v228
	v_exp_f32_e32 v229, v229
	v_exp_f32_e32 v230, v230
	v_exp_f32_e32 v231, v231
	v_exp_f32_e32 v232, v232
	v_exp_f32_e32 v233, v233
	v_exp_f32_e32 v234, v234
	v_exp_f32_e32 v235, v235
	v_pk_mul_f32 v[76:77], v[76:77], v[68:69]
	v_pk_mul_f32 v[78:79], v[78:79], v[70:71]
	v_pk_mul_f32 v[72:73], v[72:73], v[64:65]
	v_pk_mul_f32 v[74:75], v[74:75], v[66:67]
	v_pk_fma_f32 v[228:229], v[228:229], v[178:179], v[178:179] op_sel_hi:[1,0,0]
	v_pk_fma_f32 v[230:231], v[230:231], v[178:179], v[178:179] op_sel_hi:[1,0,0]
	v_pk_fma_f32 v[232:233], v[232:233], v[178:179], v[178:179] op_sel_hi:[1,0,0]
	v_pk_fma_f32 v[234:235], v[234:235], v[178:179], v[178:179] op_sel_hi:[1,0,0]
	v_rcp_f32_e32 v228, v228
	v_rcp_f32_e32 v229, v229
	v_rcp_f32_e32 v230, v230
	v_rcp_f32_e32 v231, v231
	v_rcp_f32_e32 v232, v232
	v_rcp_f32_e32 v233, v233
	v_rcp_f32_e32 v234, v234
	v_rcp_f32_e32 v235, v235
	v_pk_mul_f32 v[76:77], v[76:77], v[228:229]
	v_pk_mul_f32 v[78:79], v[78:79], v[230:231]
	v_pk_mul_f32 v[72:73], v[72:73], v[232:233]
	v_pk_mul_f32 v[74:75], v[74:75], v[234:235]
	v_cvt_pk_bf16_f32 v236, v76, v77
	v_cvt_pk_bf16_f32 v237, v78, v79
	v_cvt_pk_bf16_f32 v238, v72, v73
	v_cvt_pk_bf16_f32 v239, v74, v75
	s_nop 0
	global_store_dwordx4 v[240:241], v[236:239], off
	v_pk_mul_f32 v[228:229], v[60:61], v[196:197] op_sel_hi:[1,0]
	v_pk_mul_f32 v[230:231], v[62:63], v[196:197] op_sel_hi:[1,0]
	v_pk_mul_f32 v[232:233], v[56:57], v[196:197] op_sel_hi:[1,0]
	v_pk_mul_f32 v[234:235], v[58:59], v[196:197] op_sel_hi:[1,0]
	v_exp_f32_e32 v228, v228
	v_exp_f32_e32 v229, v229
	v_exp_f32_e32 v230, v230
	v_exp_f32_e32 v231, v231
	v_exp_f32_e32 v232, v232
	v_exp_f32_e32 v233, v233
	v_exp_f32_e32 v234, v234
	v_exp_f32_e32 v235, v235
	v_pk_mul_f32 v[60:61], v[60:61], v[52:53]
	v_pk_mul_f32 v[62:63], v[62:63], v[54:55]
	v_pk_mul_f32 v[56:57], v[56:57], v[48:49]
	v_pk_mul_f32 v[58:59], v[58:59], v[50:51]
	v_pk_fma_f32 v[228:229], v[228:229], v[180:181], v[180:181] op_sel_hi:[1,0,0]
	v_pk_fma_f32 v[230:231], v[230:231], v[180:181], v[180:181] op_sel_hi:[1,0,0]
	v_pk_fma_f32 v[232:233], v[232:233], v[180:181], v[180:181] op_sel_hi:[1,0,0]
	v_pk_fma_f32 v[234:235], v[234:235], v[180:181], v[180:181] op_sel_hi:[1,0,0]
	v_rcp_f32_e32 v228, v228
	v_rcp_f32_e32 v229, v229
	v_rcp_f32_e32 v230, v230
	v_rcp_f32_e32 v231, v231
	v_rcp_f32_e32 v232, v232
	v_rcp_f32_e32 v233, v233
	v_rcp_f32_e32 v234, v234
	v_rcp_f32_e32 v235, v235
	v_pk_mul_f32 v[60:61], v[60:61], v[228:229]
	v_pk_mul_f32 v[62:63], v[62:63], v[230:231]
	v_pk_mul_f32 v[56:57], v[56:57], v[232:233]
	v_pk_mul_f32 v[58:59], v[58:59], v[234:235]
	v_cvt_pk_bf16_f32 v236, v60, v61
	v_cvt_pk_bf16_f32 v237, v62, v63
	v_cvt_pk_bf16_f32 v238, v56, v57
	v_cvt_pk_bf16_f32 v239, v58, v59
	s_nop 0
	global_store_dwordx4 v[242:243], v[236:239], off
	v_lshl_add_u64 v[242:243], v[242:243], 0, s[100:101]
	v_pk_mul_f32 v[228:229], v[44:45], v[198:199] op_sel_hi:[1,0]
	v_pk_mul_f32 v[230:231], v[46:47], v[198:199] op_sel_hi:[1,0]
	v_pk_mul_f32 v[232:233], v[40:41], v[198:199] op_sel_hi:[1,0]
	v_pk_mul_f32 v[234:235], v[42:43], v[198:199] op_sel_hi:[1,0]
	v_exp_f32_e32 v228, v228
	v_exp_f32_e32 v229, v229
	v_exp_f32_e32 v230, v230
	v_exp_f32_e32 v231, v231
	v_exp_f32_e32 v232, v232
	v_exp_f32_e32 v233, v233
	v_exp_f32_e32 v234, v234
	v_exp_f32_e32 v235, v235
	v_pk_mul_f32 v[44:45], v[44:45], v[36:37]
	v_pk_mul_f32 v[46:47], v[46:47], v[38:39]
	v_pk_mul_f32 v[40:41], v[40:41], v[32:33]
	v_pk_mul_f32 v[42:43], v[42:43], v[34:35]
	v_pk_fma_f32 v[228:229], v[228:229], v[182:183], v[182:183] op_sel_hi:[1,0,0]
	v_pk_fma_f32 v[230:231], v[230:231], v[182:183], v[182:183] op_sel_hi:[1,0,0]
	v_pk_fma_f32 v[232:233], v[232:233], v[182:183], v[182:183] op_sel_hi:[1,0,0]
	v_pk_fma_f32 v[234:235], v[234:235], v[182:183], v[182:183] op_sel_hi:[1,0,0]
	v_rcp_f32_e32 v228, v228
; __device__ __forceinline__ unsigned pk2(float lo, float hi) { f32x2_t v = {lo, hi}; bf16x2_t b = __builtin_convertvector(v, bf16x2_t); return __builtin_bit_cast(unsigned, b); }
; __device__ __forceinline__ float sigm(float x) { return frcp(1.f + fexp2(-LOG2E * x)); }
;   __device__ __forceinline__ void operator()(const pg8::f32x4 (&acc)[2][2][4][2], const pg8::Unit& u, int wr, int wc, int fr, int fq) const {
;     ...
;       for (int m = 0; m < 4; ++m) {
;         const float r = rs[m]; float v[8];
; #pragma unroll
;         for (int n = 0; n < 2; ++n)
; #pragma unroll
;           for (int c = 0; c < 4; ++c) { const float g = acc[ai][0][m][n][c] * r, uu = acc[ai][1][m][n][c] * r; v[4 * n + c] = g * sigm(g) * uu; }
;         u32x4 w; w.x = pk2(v[0], v[1]); w.y = pk2(v[2], v[3]); w.z = pk2(v[4], v[5]); w.w = pk2(v[6], v[7]);
;         *(u32x4*)(hbuf + (unsigned)(row0 + ai * 128 + m * 16) * DFF + col0) = w;
	v_rcp_f32_e32 v229, v229
	v_rcp_f32_e32 v230, v230
	v_rcp_f32_e32 v231, v231
	v_rcp_f32_e32 v232, v232
	v_rcp_f32_e32 v233, v233
	v_rcp_f32_e32 v234, v234
	v_rcp_f32_e32 v235, v235
	v_pk_mul_f32 v[44:45], v[44:45], v[228:229]
	v_pk_mul_f32 v[46:47], v[46:47], v[230:231]
	v_pk_mul_f32 v[40:41], v[40:41], v[232:233]
	v_pk_mul_f32 v[42:43], v[42:43], v[234:235]
	v_cvt_pk_bf16_f32 v236, v44, v45
	v_cvt_pk_bf16_f32 v237, v46, v47
	v_cvt_pk_bf16_f32 v238, v40, v41
	v_cvt_pk_bf16_f32 v239, v42, v43
	s_nop 0
	global_store_dwordx4 v[242:243], v[236:239], off
	v_lshl_add_u64 v[242:243], v[242:243], 0, s[100:101]
	v_pk_mul_f32 v[228:229], v[28:29], v[200:201] op_sel_hi:[1,0]
	v_pk_mul_f32 v[230:231], v[30:31], v[200:201] op_sel_hi:[1,0]
	v_pk_mul_f32 v[232:233], v[24:25], v[200:201] op_sel_hi:[1,0]
	v_pk_mul_f32 v[234:235], v[26:27], v[200:201] op_sel_hi:[1,0]
	v_exp_f32_e32 v228, v228
	v_exp_f32_e32 v229, v229
	v_exp_f32_e32 v230, v230
	v_exp_f32_e32 v231, v231
	v_exp_f32_e32 v232, v232
	v_exp_f32_e32 v233, v233
	v_exp_f32_e32 v234, v234
	v_exp_f32_e32 v235, v235
	v_pk_mul_f32 v[28:29], v[28:29], v[20:21]
	v_pk_mul_f32 v[30:31], v[30:31], v[22:23]
	v_pk_mul_f32 v[24:25], v[24:25], v[16:17]
	v_pk_mul_f32 v[26:27], v[26:27], v[18:19]
	v_pk_fma_f32 v[228:229], v[228:229], v[184:185], v[184:185] op_sel_hi:[1,0,0]
	v_pk_fma_f32 v[230:231], v[230:231], v[184:185], v[184:185] op_sel_hi:[1,0,0]
	v_pk_fma_f32 v[232:233], v[232:233], v[184:185], v[184:185] op_sel_hi:[1,0,0]
	v_pk_fma_f32 v[234:235], v[234:235], v[184:185], v[184:185] op_sel_hi:[1,0,0]
	v_rcp_f32_e32 v228, v228
	v_rcp_f32_e32 v229, v229
	v_rcp_f32_e32 v230, v230
	v_rcp_f32_e32 v231, v231
	v_rcp_f32_e32 v232, v232
	v_rcp_f32_e32 v233, v233
	v_rcp_f32_e32 v234, v234
	v_rcp_f32_e32 v235, v235
	v_pk_mul_f32 v[28:29], v[28:29], v[228:229]
	v_pk_mul_f32 v[30:31], v[30:31], v[230:231]
	v_pk_mul_f32 v[24:25], v[24:25], v[232:233]
	v_pk_mul_f32 v[26:27], v[26:27], v[234:235]
	v_cvt_pk_bf16_f32 v236, v28, v29
	v_cvt_pk_bf16_f32 v237, v30, v31
	v_cvt_pk_bf16_f32 v238, v24, v25
	v_cvt_pk_bf16_f32 v239, v26, v27
	s_nop 0
	global_store_dwordx4 v[242:243], v[236:239], off
	v_lshl_add_u64 v[242:243], v[242:243], 0, s[100:101]
	v_pk_mul_f32 v[228:229], v[12:13], v[202:203] op_sel_hi:[1,0]
	v_pk_mul_f32 v[230:231], v[14:15], v[202:203] op_sel_hi:[1,0]
	v_pk_mul_f32 v[232:233], v[8:9], v[202:203] op_sel_hi:[1,0]
	v_pk_mul_f32 v[234:235], v[10:11], v[202:203] op_sel_hi:[1,0]
	v_exp_f32_e32 v228, v228
	v_exp_f32_e32 v229, v229
	v_exp_f32_e32 v230, v230
	v_exp_f32_e32 v231, v231
	v_exp_f32_e32 v232, v232
	v_exp_f32_e32 v233, v233
	v_exp_f32_e32 v234, v234
	v_exp_f32_e32 v235, v235
	v_pk_mul_f32 v[12:13], v[12:13], v[4:5]
	v_pk_mul_f32 v[14:15], v[14:15], v[6:7]
	v_pk_mul_f32 v[8:9], v[8:9], v[0:1]
	v_pk_mul_f32 v[10:11], v[10:11], v[2:3]
	v_pk_fma_f32 v[228:229], v[228:229], v[186:187], v[186:187] op_sel_hi:[1,0,0]
	v_pk_fma_f32 v[230:231], v[230:231], v[186:187], v[186:187] op_sel_hi:[1,0,0]
	v_pk_fma_f32 v[232:233], v[232:233], v[186:187], v[186:187] op_sel_hi:[1,0,0]
	v_pk_fma_f32 v[234:235], v[234:235], v[186:187], v[186:187] op_sel_hi:[1,0,0]
	v_rcp_f32_e32 v228, v228
	v_rcp_f32_e32 v229, v229
	v_rcp_f32_e32 v230, v230
	v_rcp_f32_e32 v231, v231
	v_rcp_f32_e32 v232, v232
	v_rcp_f32_e32 v233, v233
	v_rcp_f32_e32 v234, v234
	v_rcp_f32_e32 v235, v235
	v_pk_mul_f32 v[12:13], v[12:13], v[228:229]
	v_pk_mul_f32 v[14:15], v[14:15], v[230:231]
	v_pk_mul_f32 v[8:9], v[8:9], v[232:233]
	v_pk_mul_f32 v[10:11], v[10:11], v[234:235]
	v_cvt_pk_bf16_f32 v236, v12, v13
	v_cvt_pk_bf16_f32 v237, v14, v15
	v_cvt_pk_bf16_f32 v238, v8, v9
	v_cvt_pk_bf16_f32 v239, v10, v11
	s_nop 0
	global_store_dwordx4 v[242:243], v[236:239], off
	s_andn2_b64 vcc, exec, s[6:7]
	s_mov_b64 s[6:7], -1
	s_cbranch_vccnz .LBB0_764
	s_andn2_b64 vcc, exec, s[14:15]
	s_cbranch_vccnz .LBB0_763
	s_barrier
	s_branch .LBB0_763

; template <class Epi, class Sched, bool ALIGN_EPI = false, bool SP2 = false, bool F16 = false, bool TOKPERM = false>
; __device__ __forceinline__ void gemm_phase(PG8_LAS unsigned char* lds, const Gemm g, const Sched& S, const Epi& E, int wv) {
;     int tid_ = wv * 64 + lane_id(); asm volatile("" : "+v"(tid_));
;     const int tid = tid_, wid = __builtin_amdgcn_readfirstlane(tid >> 6), lane = tid & 63, wr = wid >> 2, wc = wid & 3, fr = lane & 15, fq = lane >> 4;
;     const int K = g.K, nt = K / BK;
;     unsigned voffA[2], voffB[2];
; #pragma unroll
;     for (int i = 0; i < 2; ++i) { int R, C; stage_rc(tid * 16 + i * 8192, R, C); const int Rb = Epi::PERM ? ((R & ~31) + perm32(R & 31)) : R;
;         const int Ra = TOKPERM ? ((R & ~63) + 4 * (R & 15) + ((R >> 4) & 3)) : R;
;         voffA[i] = (unsigned)(Ra * K + C) * 2u; voffB[i] = (unsigned)(Rb * K + C) * 2u; }
;     const size_t kstep = (size_t)(BK * 2);
;     const size_t hstep = (size_t)HALF * K * 2;
;     const size_t tstep = 2 * hstep;
;     const unsigned ldsw = (unsigned)wid * 1024u;
;     const int aoff = lds_byte(wr * 64 + fr, fq * 8), boff = lds_byte(wc * 32 + fr, fq * 8);
;     ...
;     Unit cur, nxt; int ui = 0;
;     if (!S.next(0, cur)) return;
;     f32x4 acc[2][2][4][2];
; #pragma unroll
;     for (int a = 0; a < 2; ++a)
; #pragma unroll
;         for (int b = 0; b < 2; ++b)
; #pragma unroll
;             for (int m = 0; m < 4; ++m)
; #pragma unroll
;                 for (int n = 0; n < 2; ++n) acc[a][b][m][n] = (f32x4){0.f, 0.f, 0.f, 0.f};
;     bf16x8 At[4][2], B0[2][2], B1[2][2];
;     const char* cA = (const char*)g.A + (size_t)cur.pm * tstep; const char* cB = (const char*)g.Bt + (size_t)cur.pn * tstep;
;     S.a_ready(cur);
;     if constexpr (SP2) {
;         PG8_STAGE(PG8_SB(0, 0), cB, voffB); PG8_STAGE(PG8_SB(0, 1), cB + hstep, voffB); PG8_STAGE(PG8_SA(0, 0), cA, voffA); PG8_STAGE(PG8_SA(0, 1), cA + hstep, voffA);
;         if (wr == 1) PG8_BAR;
;         PG8_WAIT_V(2); PG8_BAR;
;         PG8_STAGE(PG8_SB(1, 0), cB + kstep, voffB); PG8_STAGE(PG8_SA(1, 0), cA + kstep, voffA); PG8_STAGE(PG8_SB(1, 1), cB + hstep + kstep, voffB);
;         PG8_WAIT_V(6); PG8_BAR;
;     } else {
;         PG8_STAGE(PG8_SB(0, 0), cB, voffB); PG8_STAGE(PG8_SA(0, 0), cA, voffA); PG8_STAGE(PG8_SB(0, 1), cB + hstep, voffB); PG8_STAGE(PG8_SA(0, 1), cA + hstep, voffA);
;         if (wr == 1) PG8_BAR;
.LBB0_944:
	s_lshl_b32 s9, s16, 5
	s_add_i32 s58, s2, 0x18000
	s_mov_b64 s[16:17], 0x80
	s_and_b32 s20, s9, 0x60
	v_lshl_add_u64 v[6:7], v[6:7], 0, s[16:17]
	s_mov_b32 m0, s58
	s_add_i32 s59, s2, 0x1a000
	s_lshl_b32 s19, s18, 13
	s_lshl_b32 s22, s20, 7
	s_waitcnt vmcnt(2)
	s_barrier
	global_load_lds_dwordx4 v[6:7], off
	v_lshl_add_u64 v[4:5], v[4:5], 0, s[16:17]
	s_mov_b32 m0, s59
	s_add_i32 s60, s2, 0x8000
	s_add_i32 s61, s2, 0xa000
	global_load_lds_dwordx4 v[4:5], off
	v_lshl_add_u64 v[0:1], v[0:1], 0, s[16:17]
	s_mov_b32 m0, s60
	s_add_u32 s48, s12, 0x40080
	global_load_lds_dwordx4 v[0:1], off
	v_lshl_add_u64 v[0:1], v[2:3], 0, s[16:17]
	s_mov_b32 m0, s61
	s_addc_u32 s49, s13, 0
	s_add_i32 s62, s2, 0x1c000
	global_load_lds_dwordx4 v[0:1], off
	v_lshl_add_u64 v[0:1], s[48:49], 0, v[132:133]
	s_mov_b32 m0, s62
	s_add_i32 s63, s2, 0x1e000
	global_load_lds_dwordx4 v[0:1], off
	v_lshl_add_u64 v[0:1], s[48:49], 0, v[128:129]
	s_mov_b32 m0, s63
	v_lshlrev_b32_e32 v2, 2, v10
	global_load_lds_dwordx4 v[0:1], off
	v_bfe_u32 v1, v10, 4, 2
	v_and_b32_e32 v0, 15, v10
	v_lshlrev_b32_e32 v136, 4, v1
	v_lshl_or_b32 v154, v1, 3, s20
	v_lshlrev_b32_e32 v1, 14, v13
	v_lshl_or_b32 v151, s18, 6, v0
	v_lshl_or_b32 v0, v0, 6, v136
	v_and_b32_e32 v2, 32, v2
	v_and_b32_e32 v1, 0xffff8000, v1
	v_bitop3_b32 v153, v0, s19, v2 bitop3:0xde
	v_bitop3_b32 v0, v0, s22, v2 bitop3:0xde
	v_lshl_add_u32 v1, v12, 11, v1
	v_and_b32_e32 v2, 1, v13
	v_lshl_or_b32 v1, v2, 6, v1
	v_lshl_add_u32 v140, v14, 1, v1
	v_lshlrev_b32_e32 v1, 14, v8
	v_and_b32_e32 v1, 0xffff8000, v1
	s_waitcnt vmcnt(6)
	v_lshl_add_u32 v1, v9, 11, v1
	v_and_b32_e32 v2, 1, v8
	s_cmpk_lt_u32 s7, 0x100
	v_lshl_or_b32 v1, v2, 6, v1
	s_sext_i32_i16 s9, s6
	s_cselect_b64 s[18:19], -1, 0
	v_lshl_add_u64 v[138:139], s[42:43], 0, v[136:137]
	s_ashr_i32 s64, s28, 31
	s_mov_b32 s65, s28
	v_mov_b32_e32 v141, v137
	v_lshl_add_u32 v142, v11, 1, v1
	v_mov_b32_e32 v143, v137
	v_mov_b64_e32 v[144:145], 0x580
	v_mov_b64_e32 v[146:147], 0x57f
	v_or_b32_e32 v155, 0x10000, v0
	v_add_u32_e32 v156, 0x10400, v0
	v_add_u32_e32 v157, 0x10800, v0
	v_add_u32_e32 v158, 0x10c00, v0
	v_or_b32_e32 v159, 0x14000, v0
	v_add_u32_e32 v160, 0x14400, v0
	v_add_u32_e32 v161, 0x14800, v0
	v_add_u32_e32 v162, 0x14c00, v0
	s_add_i32 s66, s2, 0xc000
	s_add_i32 s67, s2, 0xe000
	v_or_b32_e32 v163, 0x18000, v0
	v_add_u32_e32 v164, 0x18400, v0
	v_add_u32_e32 v165, 0x18800, v0
	v_add_u32_e32 v166, 0x18c00, v0
	v_or_b32_e32 v167, 0x1c000, v0
	v_add_u32_e32 v168, 0x1c400, v0
	v_add_u32_e32 v169, 0x1c800, v0
	v_add_u32_e32 v170, 0x1cc00, v0
	v_mbcnt_hi_u32_b32 v171, -1, v226
	s_mov_b32 s20, 0x3a800000
	s_mov_b32 s22, 0x358637bd
	s_mov_b32 s68, 0x800000
	s_movk_i32 s69, 0xb00
	s_barrier
	s_mov_b32 s99, -1
	s_branch .LBB0_947

; template <class Epi, class Sched, bool ALIGN_EPI = false, bool SP2 = false, bool F16 = false, bool TOKPERM = false>
; __device__ __forceinline__ void gemm_phase(PG8_LAS unsigned char* lds, const Gemm g, const Sched& S, const Epi& E, int wv) {
;     int tid_ = wv * 64 + lane_id(); asm volatile("" : "+v"(tid_));
;     const int tid = tid_, wid = __builtin_amdgcn_readfirstlane(tid >> 6), lane = tid & 63, wr = wid >> 2, wc = wid & 3, fr = lane & 15, fq = lane >> 4;
;     const int K = g.K, nt = K / BK;
;     unsigned voffA[2], voffB[2];
; #pragma unroll
;     for (int i = 0; i < 2; ++i) { int R, C; stage_rc(tid * 16 + i * 8192, R, C); const int Rb = Epi::PERM ? ((R & ~31) + perm32(R & 31)) : R;
;         const int Ra = TOKPERM ? ((R & ~63) + 4 * (R & 15) + ((R >> 4) & 3)) : R;
;         voffA[i] = (unsigned)(Ra * K + C) * 2u; voffB[i] = (unsigned)(Rb * K + C) * 2u; }
;     const size_t kstep = (size_t)(BK * 2);
;     const size_t hstep = (size_t)HALF * K * 2;
;     const size_t tstep = 2 * hstep;
;     const unsigned ldsw = (unsigned)wid * 1024u;
;     const int aoff = lds_byte(wr * 64 + fr, fq * 8), boff = lds_byte(wc * 32 + fr, fq * 8);
;     ...
;     Unit cur, nxt; int ui = 0;
;     if (!S.next(0, cur)) return;
;     f32x4 acc[2][2][4][2];
; #pragma unroll
;     for (int a = 0; a < 2; ++a)
; #pragma unroll
;         for (int b = 0; b < 2; ++b)
; #pragma unroll
;             for (int m = 0; m < 4; ++m)
; #pragma unroll
;                 for (int n = 0; n < 2; ++n) acc[a][b][m][n] = (f32x4){0.f, 0.f, 0.f, 0.f};
;     bf16x8 At[4][2], B0[2][2], B1[2][2];
;     const char* cA = (const char*)g.A + (size_t)cur.pm * tstep; const char* cB = (const char*)g.Bt + (size_t)cur.pn * tstep;
;     S.a_ready(cur);
;     if constexpr (SP2) {
;         PG8_STAGE(PG8_SB(0, 0), cB, voffB); PG8_STAGE(PG8_SB(0, 1), cB + hstep, voffB); PG8_STAGE(PG8_SA(0, 0), cA, voffA); PG8_STAGE(PG8_SA(0, 1), cA + hstep, voffA);
;         if (wr == 1) PG8_BAR;
;         PG8_WAIT_V(2); PG8_BAR;
;         PG8_STAGE(PG8_SB(1, 0), cB + kstep, voffB); PG8_STAGE(PG8_SA(1, 0), cA + kstep, voffA); PG8_STAGE(PG8_SB(1, 1), cB + hstep + kstep, voffB);
;         PG8_WAIT_V(6); PG8_BAR;
;     } else {
;         PG8_STAGE(PG8_SB(0, 0), cB, voffB); PG8_STAGE(PG8_SA(0, 0), cA, voffA); PG8_STAGE(PG8_SB(0, 1), cB + hstep, voffB); PG8_STAGE(PG8_SA(0, 1), cA + hstep, voffA);
;         if (wr == 1) PG8_BAR;
.LBB0_1601:
	s_lshl_b32 s7, s14, 5
	s_add_i32 s52, s2, 0x18000
	s_mov_b64 s[14:15], 0x80
	s_and_b32 s18, s7, 0x60
	v_lshl_add_u64 v[6:7], v[6:7], 0, s[14:15]
	s_mov_b32 m0, s52
	s_add_i32 s53, s2, 0x1a000
	s_lshl_b32 s17, s16, 13
	s_lshl_b32 s20, s18, 7
	s_waitcnt vmcnt(2)
	s_barrier
	global_load_lds_dwordx4 v[6:7], off
	v_lshl_add_u64 v[4:5], v[4:5], 0, s[14:15]
	s_mov_b32 m0, s53
	s_add_i32 s54, s2, 0x8000
	s_add_i32 s55, s2, 0xa000
	global_load_lds_dwordx4 v[4:5], off
	v_lshl_add_u64 v[0:1], v[0:1], 0, s[14:15]
	s_mov_b32 m0, s54
	s_add_u32 s22, s10, 0x40080
	global_load_lds_dwordx4 v[0:1], off
	v_lshl_add_u64 v[0:1], v[2:3], 0, s[14:15]
	s_mov_b32 m0, s55
	s_addc_u32 s23, s11, 0
	s_add_i32 s56, s2, 0x1c000
	global_load_lds_dwordx4 v[0:1], off
	v_lshl_add_u64 v[0:1], s[22:23], 0, v[132:133]
	s_mov_b32 m0, s56
	s_add_i32 s57, s2, 0x1e000
	global_load_lds_dwordx4 v[0:1], off
	v_lshl_add_u64 v[0:1], s[22:23], 0, v[128:129]
	s_mov_b32 m0, s57
	v_lshlrev_b32_e32 v2, 2, v10
	global_load_lds_dwordx4 v[0:1], off
	v_bfe_u32 v1, v10, 4, 2
	v_and_b32_e32 v0, 15, v10
	v_lshlrev_b32_e32 v136, 4, v1
	v_lshl_or_b32 v154, v1, 3, s18
	v_lshlrev_b32_e32 v1, 14, v13
	v_lshl_or_b32 v151, s16, 6, v0
	v_lshl_or_b32 v0, v0, 6, v136
	v_and_b32_e32 v2, 32, v2
	v_and_b32_e32 v1, 0xffff8000, v1
	v_bitop3_b32 v153, v0, s17, v2 bitop3:0xde
	v_bitop3_b32 v0, v0, s20, v2 bitop3:0xde
	v_lshl_add_u32 v1, v12, 11, v1
	v_and_b32_e32 v2, 1, v13
	v_lshl_or_b32 v1, v2, 6, v1
	v_lshl_add_u32 v140, v14, 1, v1
	v_lshlrev_b32_e32 v1, 14, v8
	v_and_b32_e32 v1, 0xffff8000, v1
	s_waitcnt vmcnt(6)
	v_lshl_add_u32 v1, v9, 11, v1
	v_and_b32_e32 v2, 1, v8
	s_cmpk_lt_u32 s5, 0x100
	v_lshl_or_b32 v1, v2, 6, v1
	s_sext_i32_i16 s7, s4
	s_cselect_b64 s[16:17], -1, 0
	v_lshl_add_u64 v[138:139], s[42:43], 0, v[136:137]
	s_ashr_i32 s58, s28, 31
	s_mov_b32 s59, s28
	v_mov_b32_e32 v141, v137
	v_lshl_add_u32 v142, v11, 1, v1
	v_mov_b32_e32 v143, v137
	v_mov_b64_e32 v[144:145], 0x580
	v_mov_b64_e32 v[146:147], 0x57f
	v_or_b32_e32 v155, 0x10000, v0
	v_add_u32_e32 v156, 0x10400, v0
	v_add_u32_e32 v157, 0x10800, v0
	v_add_u32_e32 v158, 0x10c00, v0
	v_or_b32_e32 v159, 0x14000, v0
	s_waitcnt vmcnt(0)
	v_add_u32_e32 v160, 0x14400, v0
	v_add_u32_e32 v161, 0x14800, v0
	v_add_u32_e32 v162, 0x14c00, v0
	s_add_i32 s60, s2, 0xc000
	s_add_i32 s61, s2, 0xe000
	v_or_b32_e32 v163, 0x18000, v0
	v_add_u32_e32 v164, 0x18400, v0
	v_add_u32_e32 v165, 0x18800, v0
	v_add_u32_e32 v166, 0x18c00, v0
	v_or_b32_e32 v167, 0x1c000, v0
	v_add_u32_e32 v168, 0x1c400, v0
	v_add_u32_e32 v169, 0x1c800, v0
	v_add_u32_e32 v170, 0x1cc00, v0
	v_mbcnt_hi_u32_b32 v171, -1, v226
	s_mov_b32 s18, 0x3a800000
	s_mov_b32 s20, 0x358637bd
	s_mov_b32 s62, 0x800000
	s_movk_i32 s63, 0xb00
	s_barrier
	s_mov_b32 s99, -1
	s_branch .LBB0_1604

;   __device__ __forceinline__ void operator()(const pg8::f32x4 (&acc)[2][2][4][2], const pg8::Unit& u, int wr, int wc, int fr, int fq) const {
;     ...
;     const int row0 = u.pm * 256 + wr * 64 + fr + z, col0 = u.pn * 128 + wc * 32 + 8 * fq + z;
; #pragma unroll
;     for (int ai = 0; ai < 2; ++ai) {
;       float rs[4];
; #pragma unroll
;       for (int m = 0; m < 4; ++m) { const f32x4 a = *(const f32x4*)(ssq + (unsigned)(row0 + ai * 128 + m * 16) * 16 + 4 * fq); rs[m] = (a[0] + a[1]) + (a[2] + a[3]); }
; #pragma unroll
;       for (int m = 0; m < 4; ++m) { float v = rs[m]; v += __shfl_xor(v, 16); v += __shfl_xor(v, 32); rs[m] = rsqrtf(v * (1.f / 1024.f) + EPS); }
.LBB0_1610:
	s_lshl_b32 s6, s6, 8
	s_cmp_eq_u32 s6, s99
	s_mov_b32 s98, 0x3a800000
	s_mov_b32 s100, 0xb0000
	s_mov_b32 s101, 0
	v_add_u32_e32 v148, s6, v151
	v_lshl_or_b32 v152, s7, 7, v154
	v_mul_u32_u24_e32 v136, 0xb00, v148
	v_mov_b32_e32 v150, 0x358637bd
	v_add_u32_e32 v136, v136, v152
	v_lshl_add_u64 v[240:241], v[136:137], 1, s[38:39]
	s_cbranch_scc1 .Lgu_1607_cached
	v_lshlrev_b32_e32 v136, 4, v148
	v_lshl_add_u64 v[242:243], v[136:137], 2, v[138:139]
	global_load_dwordx4 v[172:175], v[242:243], off
	global_load_dwordx4 v[176:179], v[242:243], off offset:1024
	global_load_dwordx4 v[180:183], v[242:243], off offset:2048
	global_load_dwordx4 v[184:187], v[242:243], off offset:3072
	v_add_u32_e32 v136, 0x800, v136
	v_lshl_add_u64 v[242:243], v[136:137], 2, v[138:139]
	global_load_dwordx4 v[188:191], v[242:243], off
	global_load_dwordx4 v[192:195], v[242:243], off offset:1024
	global_load_dwordx4 v[196:199], v[242:243], off offset:2048
	global_load_dwordx4 v[200:203], v[242:243], off offset:3072
	s_waitcnt vmcnt(0)
	v_add_f32_e32 v204, v172, v173
	v_add_f32_e32 v228, v174, v175
	v_add_f32_e32 v205, v176, v177
	v_add_f32_e32 v229, v178, v179
	v_add_f32_e32 v206, v180, v181
	v_add_f32_e32 v230, v182, v183
	v_add_f32_e32 v207, v184, v185
	v_add_f32_e32 v231, v186, v187
	v_add_f32_e32 v208, v188, v189
	v_add_f32_e32 v232, v190, v191
	v_add_f32_e32 v209, v192, v193
	v_add_f32_e32 v233, v194, v195
	v_add_f32_e32 v210, v196, v197
	v_add_f32_e32 v234, v198, v199
	v_add_f32_e32 v211, v200, v201
	v_add_f32_e32 v235, v202, v203
	v_add_f32_e32 v204, v204, v228
	v_add_f32_e32 v205, v205, v229
	v_add_f32_e32 v206, v206, v230
	v_add_f32_e32 v207, v207, v231
	v_add_f32_e32 v208, v208, v232
	v_add_f32_e32 v209, v209, v233
	v_add_f32_e32 v210, v210, v234
	v_add_f32_e32 v211, v211, v235
	v_mov_b32_e32 v228, v204
	v_mov_b32_e32 v229, v205
	v_mov_b32_e32 v230, v206
	v_mov_b32_e32 v231, v207
	v_mov_b32_e32 v232, v208
	v_mov_b32_e32 v233, v209
	v_mov_b32_e32 v234, v210
	v_mov_b32_e32 v235, v211
	v_permlane16_swap_b32_e32 v204, v228
	v_permlane16_swap_b32_e32 v205, v229
	v_permlane16_swap_b32_e32 v206, v230
	v_permlane16_swap_b32_e32 v207, v231
	v_permlane16_swap_b32_e32 v208, v232
	v_permlane16_swap_b32_e32 v209, v233
	v_permlane16_swap_b32_e32 v210, v234
	v_permlane16_swap_b32_e32 v211, v235
	v_add_f32_e32 v204, v204, v228
	v_add_f32_e32 v205, v205, v229
	v_add_f32_e32 v206, v206, v230
	v_add_f32_e32 v207, v207, v231
	v_add_f32_e32 v208, v208, v232
	v_add_f32_e32 v209, v209, v233
	v_add_f32_e32 v210, v210, v234
	v_add_f32_e32 v211, v211, v235
	v_mov_b32_e32 v228, v204
	v_mov_b32_e32 v229, v205
	v_mov_b32_e32 v230, v206
	v_mov_b32_e32 v231, v207
	v_mov_b32_e32 v232, v208
	v_mov_b32_e32 v233, v209
	v_mov_b32_e32 v234, v210
	v_mov_b32_e32 v235, v211
	v_permlane32_swap_b32_e32 v204, v228
	v_permlane32_swap_b32_e32 v205, v229
	v_permlane32_swap_b32_e32 v206, v230
	v_permlane32_swap_b32_e32 v207, v231
	v_permlane32_swap_b32_e32 v208, v232
	v_permlane32_swap_b32_e32 v209, v233
	v_permlane32_swap_b32_e32 v210, v234
	v_permlane32_swap_b32_e32 v211, v235
	v_add_f32_e32 v204, v204, v228
	v_add_f32_e32 v205, v205, v229
	v_add_f32_e32 v206, v206, v230
	v_add_f32_e32 v207, v207, v231
	v_add_f32_e32 v208, v208, v232
	v_add_f32_e32 v209, v209, v233
	v_add_f32_e32 v210, v210, v234
	v_add_f32_e32 v211, v211, v235
	v_fma_f32 v172, v204, s98, v150
	v_fma_f32 v174, v205, s98, v150
	v_fma_f32 v176, v206, s98, v150
	v_fma_f32 v178, v207, s98, v150
	v_fma_f32 v180, v208, s98, v150
	v_fma_f32 v182, v209, s98, v150
	v_fma_f32 v184, v210, s98, v150
	v_fma_f32 v186, v211, s98, v150
	v_mov_b32_e32 v246, v172
	v_mov_b32_e32 v247, v174
	v_mov_b32_e32 v248, v176
	v_mov_b32_e32 v249, v178
	v_mov_b32_e32 v250, v180
	v_mov_b32_e32 v251, v182
	v_mov_b32_e32 v253, v184
	v_mov_b32_e32 v254, v186
	s_mov_b32 s99, s6
	s_branch .Lgu_1607_havew

; __device__ __forceinline__ unsigned pk2(float lo, float hi) { f32x2_t v = {lo, hi}; bf16x2_t b = __builtin_convertvector(v, bf16x2_t); return __builtin_bit_cast(unsigned, b); }
; __device__ __forceinline__ float sigm(float x) { return frcp(1.f + fexp2(-LOG2E * x)); }
;   __device__ __forceinline__ void operator()(const pg8::f32x4 (&acc)[2][2][4][2], const pg8::Unit& u, int wr, int wc, int fr, int fq) const {
;     ...
;       for (int m = 0; m < 4; ++m) { float v = rs[m]; v += __shfl_xor(v, 16); v += __shfl_xor(v, 32); rs[m] = rsqrtf(v * (1.f / 1024.f) + EPS); }
; #pragma unroll
;       for (int m = 0; m < 4; ++m) {
;         const float r = rs[m]; float v[8];
; #pragma unroll
;         for (int n = 0; n < 2; ++n)
; #pragma unroll
;           for (int c = 0; c < 4; ++c) { const float g = acc[ai][0][m][n][c] * r, uu = acc[ai][1][m][n][c] * r; v[4 * n + c] = g * sigm(g) * uu; }
;         u32x4 w; w.x = pk2(v[0], v[1]); w.y = pk2(v[2], v[3]); w.z = pk2(v[4], v[5]); w.w = pk2(v[6], v[7]);
;         *(u32x4*)(hbuf + (unsigned)(row0 + ai * 128 + m * 16) * DFF + col0) = w;
.Lgu_1607_havew:
	v_lshl_add_u64 v[242:243], v[240:241], 0, s[100:101]
	s_mov_b32 s100, 0x16000
	v_rsq_f32_e32 v188, v172
	v_rsq_f32_e32 v190, v174
	v_rsq_f32_e32 v192, v176
	v_rsq_f32_e32 v194, v178
	v_rsq_f32_e32 v196, v180
	v_rsq_f32_e32 v198, v182
	v_rsq_f32_e32 v200, v184
	v_rsq_f32_e32 v202, v186
	v_mul_f32_e32 v188, 0xbfb8aa3b, v188
	v_mul_f32_e32 v190, 0xbfb8aa3b, v190
	v_mul_f32_e32 v192, 0xbfb8aa3b, v192
	v_mul_f32_e32 v194, 0xbfb8aa3b, v194
	v_mul_f32_e32 v196, 0xbfb8aa3b, v196
	v_mul_f32_e32 v198, 0xbfb8aa3b, v198
	v_mul_f32_e32 v200, 0xbfb8aa3b, v200
	v_mul_f32_e32 v202, 0xbfb8aa3b, v202
	v_pk_mul_f32 v[228:229], v[124:125], v[188:189] op_sel_hi:[1,0]
	v_pk_mul_f32 v[230:231], v[126:127], v[188:189] op_sel_hi:[1,0]
	v_pk_mul_f32 v[232:233], v[116:117], v[188:189] op_sel_hi:[1,0]
	v_pk_mul_f32 v[234:235], v[118:119], v[188:189] op_sel_hi:[1,0]
	v_exp_f32_e32 v228, v228
	v_exp_f32_e32 v229, v229
	v_exp_f32_e32 v230, v230
	v_exp_f32_e32 v231, v231
	v_exp_f32_e32 v232, v232
	v_exp_f32_e32 v233, v233
	v_exp_f32_e32 v234, v234
	v_exp_f32_e32 v235, v235
	v_pk_mul_f32 v[124:125], v[124:125], v[120:121]
	v_pk_mul_f32 v[126:127], v[126:127], v[122:123]
	v_pk_mul_f32 v[116:117], v[116:117], v[112:113]
	v_pk_mul_f32 v[118:119], v[118:119], v[114:115]
	v_pk_fma_f32 v[228:229], v[228:229], v[172:173], v[172:173] op_sel_hi:[1,0,0]
	v_pk_fma_f32 v[230:231], v[230:231], v[172:173], v[172:173] op_sel_hi:[1,0,0]
	v_pk_fma_f32 v[232:233], v[232:233], v[172:173], v[172:173] op_sel_hi:[1,0,0]
	v_pk_fma_f32 v[234:235], v[234:235], v[172:173], v[172:173] op_sel_hi:[1,0,0]
	v_rcp_f32_e32 v228, v228
	v_rcp_f32_e32 v229, v229
	v_rcp_f32_e32 v230, v230
	v_rcp_f32_e32 v231, v231
	v_rcp_f32_e32 v232, v232
	v_rcp_f32_e32 v233, v233
	v_rcp_f32_e32 v234, v234
	v_rcp_f32_e32 v235, v235
	v_pk_mul_f32 v[124:125], v[124:125], v[228:229]
	v_pk_mul_f32 v[126:127], v[126:127], v[230:231]
	v_pk_mul_f32 v[116:117], v[116:117], v[232:233]
	v_pk_mul_f32 v[118:119], v[118:119], v[234:235]
	v_cvt_pk_bf16_f32 v236, v124, v125
	v_cvt_pk_bf16_f32 v237, v126, v127
	v_cvt_pk_bf16_f32 v238, v116, v117
	v_cvt_pk_bf16_f32 v239, v118, v119
	s_nop 0
	global_store_dwordx4 v[240:241], v[236:239], off
	v_lshl_add_u64 v[240:241], v[240:241], 0, s[100:101]
	v_pk_mul_f32 v[228:229], v[108:109], v[190:191] op_sel_hi:[1,0]
	v_pk_mul_f32 v[230:231], v[110:111], v[190:191] op_sel_hi:[1,0]
	v_pk_mul_f32 v[232:233], v[104:105], v[190:191] op_sel_hi:[1,0]
	v_pk_mul_f32 v[234:235], v[106:107], v[190:191] op_sel_hi:[1,0]
	v_exp_f32_e32 v228, v228
	v_exp_f32_e32 v229, v229
	v_exp_f32_e32 v230, v230
	v_exp_f32_e32 v231, v231
	v_exp_f32_e32 v232, v232
	v_exp_f32_e32 v233, v233
	v_exp_f32_e32 v234, v234
	v_exp_f32_e32 v235, v235
	v_pk_mul_f32 v[108:109], v[108:109], v[100:101]
	v_pk_mul_f32 v[110:111], v[110:111], v[102:103]
	v_pk_mul_f32 v[104:105], v[104:105], v[96:97]
	v_pk_mul_f32 v[106:107], v[106:107], v[98:99]
	v_pk_fma_f32 v[228:229], v[228:229], v[174:175], v[174:175] op_sel_hi:[1,0,0]
	v_pk_fma_f32 v[230:231], v[230:231], v[174:175], v[174:175] op_sel_hi:[1,0,0]
	v_pk_fma_f32 v[232:233], v[232:233], v[174:175], v[174:175] op_sel_hi:[1,0,0]
	v_pk_fma_f32 v[234:235], v[234:235], v[174:175], v[174:175] op_sel_hi:[1,0,0]
	v_rcp_f32_e32 v228, v228
	v_rcp_f32_e32 v229, v229
	v_rcp_f32_e32 v230, v230
	v_rcp_f32_e32 v231, v231
	v_rcp_f32_e32 v232, v232
	v_rcp_f32_e32 v233, v233
	v_rcp_f32_e32 v234, v234
	v_rcp_f32_e32 v235, v235
	v_pk_mul_f32 v[108:109], v[108:109], v[228:229]
	v_pk_mul_f32 v[110:111], v[110:111], v[230:231]
	v_pk_mul_f32 v[104:105], v[104:105], v[232:233]
	v_pk_mul_f32 v[106:107], v[106:107], v[234:235]
	v_cvt_pk_bf16_f32 v236, v108, v109
	v_cvt_pk_bf16_f32 v237, v110, v111
	v_cvt_pk_bf16_f32 v238, v104, v105
	v_cvt_pk_bf16_f32 v239, v106, v107
	s_nop 0
	global_store_dwordx4 v[240:241], v[236:239], off
	v_lshl_add_u64 v[240:241], v[240:241], 0, s[100:101]
	v_pk_mul_f32 v[228:229], v[92:93], v[192:193] op_sel_hi:[1,0]
	v_pk_mul_f32 v[230:231], v[94:95], v[192:193] op_sel_hi:[1,0]
	v_pk_mul_f32 v[232:233], v[88:89], v[192:193] op_sel_hi:[1,0]
	v_pk_mul_f32 v[234:235], v[90:91], v[192:193] op_sel_hi:[1,0]
	v_exp_f32_e32 v228, v228
	v_exp_f32_e32 v229, v229
	v_exp_f32_e32 v230, v230
	v_exp_f32_e32 v231, v231
	v_exp_f32_e32 v232, v232
	v_exp_f32_e32 v233, v233
	v_exp_f32_e32 v234, v234
	v_exp_f32_e32 v235, v235
	v_pk_mul_f32 v[92:93], v[92:93], v[84:85]
	v_pk_mul_f32 v[94:95], v[94:95], v[86:87]
	v_pk_mul_f32 v[88:89], v[88:89], v[80:81]
	v_pk_mul_f32 v[90:91], v[90:91], v[82:83]
	v_pk_fma_f32 v[228:229], v[228:229], v[176:177], v[176:177] op_sel_hi:[1,0,0]
	v_pk_fma_f32 v[230:231], v[230:231], v[176:177], v[176:177] op_sel_hi:[1,0,0]
	v_pk_fma_f32 v[232:233], v[232:233], v[176:177], v[176:177] op_sel_hi:[1,0,0]
	v_pk_fma_f32 v[234:235], v[234:235], v[176:177], v[176:177] op_sel_hi:[1,0,0]
	v_rcp_f32_e32 v228, v228
	v_rcp_f32_e32 v229, v229
	v_rcp_f32_e32 v230, v230
	v_rcp_f32_e32 v231, v231
	v_rcp_f32_e32 v232, v232
	v_rcp_f32_e32 v233, v233
	v_rcp_f32_e32 v234, v234
	v_rcp_f32_e32 v235, v235
	v_pk_mul_f32 v[92:93], v[92:93], v[228:229]
	v_pk_mul_f32 v[94:95], v[94:95], v[230:231]
	v_pk_mul_f32 v[88:89], v[88:89], v[232:233]
	v_pk_mul_f32 v[90:91], v[90:91], v[234:235]
	v_cvt_pk_bf16_f32 v236, v92, v93
	v_cvt_pk_bf16_f32 v237, v94, v95
	v_cvt_pk_bf16_f32 v238, v88, v89
	v_cvt_pk_bf16_f32 v239, v90, v91
	s_nop 0
	global_store_dwordx4 v[240:241], v[236:239], off
	v_lshl_add_u64 v[240:241], v[240:241], 0, s[100:101]
	v_pk_mul_f32 v[228:229], v[76:77], v[194:195] op_sel_hi:[1,0]
	v_pk_mul_f32 v[230:231], v[78:79], v[194:195] op_sel_hi:[1,0]
	v_pk_mul_f32 v[232:233], v[72:73], v[194:195] op_sel_hi:[1,0]
; __device__ __forceinline__ unsigned pk2(float lo, float hi) { f32x2_t v = {lo, hi}; bf16x2_t b = __builtin_convertvector(v, bf16x2_t); return __builtin_bit_cast(unsigned, b); }
; __device__ __forceinline__ float sigm(float x) { return frcp(1.f + fexp2(-LOG2E * x)); }
;   __device__ __forceinline__ void operator()(const pg8::f32x4 (&acc)[2][2][4][2], const pg8::Unit& u, int wr, int wc, int fr, int fq) const {
;     ...
;       for (int m = 0; m < 4; ++m) {
;         const float r = rs[m]; float v[8];
; #pragma unroll
;         for (int n = 0; n < 2; ++n)
; #pragma unroll
;           for (int c = 0; c < 4; ++c) { const float g = acc[ai][0][m][n][c] * r, uu = acc[ai][1][m][n][c] * r; v[4 * n + c] = g * sigm(g) * uu; }
;         u32x4 w; w.x = pk2(v[0], v[1]); w.y = pk2(v[2], v[3]); w.z = pk2(v[4], v[5]); w.w = pk2(v[6], v[7]);
;         *(u32x4*)(hbuf + (unsigned)(row0 + ai * 128 + m * 16) * DFF + col0) = w;
	v_pk_mul_f32 v[234:235], v[74:75], v[194:195] op_sel_hi:[1,0]
	v_exp_f32_e32 v228, v228
	v_exp_f32_e32 v229, v229
	v_exp_f32_e32 v230, v230
	v_exp_f32_e32 v231, v231
	v_exp_f32_e32 v232, v232
	v_exp_f32_e32 v233, v233
	v_exp_f32_e32 v234, v234
	v_exp_f32_e32 v235, v235
	v_pk_mul_f32 v[76:77], v[76:77], v[68:69]
	v_pk_mul_f32 v[78:79], v[78:79], v[70:71]
	v_pk_mul_f32 v[72:73], v[72:73], v[64:65]
	v_pk_mul_f32 v[74:75], v[74:75], v[66:67]
	v_pk_fma_f32 v[228:229], v[228:229], v[178:179], v[178:179] op_sel_hi:[1,0,0]
	v_pk_fma_f32 v[230:231], v[230:231], v[178:179], v[178:179] op_sel_hi:[1,0,0]
	v_pk_fma_f32 v[232:233], v[232:233], v[178:179], v[178:179] op_sel_hi:[1,0,0]
	v_pk_fma_f32 v[234:235], v[234:235], v[178:179], v[178:179] op_sel_hi:[1,0,0]
	v_rcp_f32_e32 v228, v228
	v_rcp_f32_e32 v229, v229
	v_rcp_f32_e32 v230, v230
	v_rcp_f32_e32 v231, v231
	v_rcp_f32_e32 v232, v232
	v_rcp_f32_e32 v233, v233
	v_rcp_f32_e32 v234, v234
	v_rcp_f32_e32 v235, v235
	v_pk_mul_f32 v[76:77], v[76:77], v[228:229]
	v_pk_mul_f32 v[78:79], v[78:79], v[230:231]
	v_pk_mul_f32 v[72:73], v[72:73], v[232:233]
	v_pk_mul_f32 v[74:75], v[74:75], v[234:235]
	v_cvt_pk_bf16_f32 v236, v76, v77
	v_cvt_pk_bf16_f32 v237, v78, v79
	v_cvt_pk_bf16_f32 v238, v72, v73
	v_cvt_pk_bf16_f32 v239, v74, v75
	s_nop 0
	global_store_dwordx4 v[240:241], v[236:239], off
	v_pk_mul_f32 v[228:229], v[60:61], v[196:197] op_sel_hi:[1,0]
	v_pk_mul_f32 v[230:231], v[62:63], v[196:197] op_sel_hi:[1,0]
	v_pk_mul_f32 v[232:233], v[56:57], v[196:197] op_sel_hi:[1,0]
	v_pk_mul_f32 v[234:235], v[58:59], v[196:197] op_sel_hi:[1,0]
	v_exp_f32_e32 v228, v228
	v_exp_f32_e32 v229, v229
	v_exp_f32_e32 v230, v230
	v_exp_f32_e32 v231, v231
	v_exp_f32_e32 v232, v232
	v_exp_f32_e32 v233, v233
	v_exp_f32_e32 v234, v234
	v_exp_f32_e32 v235, v235
	v_pk_mul_f32 v[60:61], v[60:61], v[52:53]
	v_pk_mul_f32 v[62:63], v[62:63], v[54:55]
	v_pk_mul_f32 v[56:57], v[56:57], v[48:49]
	v_pk_mul_f32 v[58:59], v[58:59], v[50:51]
	v_pk_fma_f32 v[228:229], v[228:229], v[180:181], v[180:181] op_sel_hi:[1,0,0]
	v_pk_fma_f32 v[230:231], v[230:231], v[180:181], v[180:181] op_sel_hi:[1,0,0]
	v_pk_fma_f32 v[232:233], v[232:233], v[180:181], v[180:181] op_sel_hi:[1,0,0]
	v_pk_fma_f32 v[234:235], v[234:235], v[180:181], v[180:181] op_sel_hi:[1,0,0]
	v_rcp_f32_e32 v228, v228
	v_rcp_f32_e32 v229, v229
	v_rcp_f32_e32 v230, v230
	v_rcp_f32_e32 v231, v231
	v_rcp_f32_e32 v232, v232
	v_rcp_f32_e32 v233, v233
	v_rcp_f32_e32 v234, v234
	v_rcp_f32_e32 v235, v235
	v_pk_mul_f32 v[60:61], v[60:61], v[228:229]
	v_pk_mul_f32 v[62:63], v[62:63], v[230:231]
	v_pk_mul_f32 v[56:57], v[56:57], v[232:233]
	v_pk_mul_f32 v[58:59], v[58:59], v[234:235]
	v_cvt_pk_bf16_f32 v236, v60, v61
	v_cvt_pk_bf16_f32 v237, v62, v63
	v_cvt_pk_bf16_f32 v238, v56, v57
	v_cvt_pk_bf16_f32 v239, v58, v59
	s_nop 0
	global_store_dwordx4 v[242:243], v[236:239], off
	v_lshl_add_u64 v[242:243], v[242:243], 0, s[100:101]
	v_pk_mul_f32 v[228:229], v[44:45], v[198:199] op_sel_hi:[1,0]
	v_pk_mul_f32 v[230:231], v[46:47], v[198:199] op_sel_hi:[1,0]
	v_pk_mul_f32 v[232:233], v[40:41], v[198:199] op_sel_hi:[1,0]
	v_pk_mul_f32 v[234:235], v[42:43], v[198:199] op_sel_hi:[1,0]
	v_exp_f32_e32 v228, v228
	v_exp_f32_e32 v229, v229
	v_exp_f32_e32 v230, v230
	v_exp_f32_e32 v231, v231
	v_exp_f32_e32 v232, v232
	v_exp_f32_e32 v233, v233
	v_exp_f32_e32 v234, v234
	v_exp_f32_e32 v235, v235
	v_pk_mul_f32 v[44:45], v[44:45], v[36:37]
	v_pk_mul_f32 v[46:47], v[46:47], v[38:39]
	v_pk_mul_f32 v[40:41], v[40:41], v[32:33]
	v_pk_mul_f32 v[42:43], v[42:43], v[34:35]
	v_pk_fma_f32 v[228:229], v[228:229], v[182:183], v[182:183] op_sel_hi:[1,0,0]
	v_pk_fma_f32 v[230:231], v[230:231], v[182:183], v[182:183] op_sel_hi:[1,0,0]
	v_pk_fma_f32 v[232:233], v[232:233], v[182:183], v[182:183] op_sel_hi:[1,0,0]
	v_pk_fma_f32 v[234:235], v[234:235], v[182:183], v[182:183] op_sel_hi:[1,0,0]
	v_rcp_f32_e32 v228, v228
; __device__ __forceinline__ unsigned pk2(float lo, float hi) { f32x2_t v = {lo, hi}; bf16x2_t b = __builtin_convertvector(v, bf16x2_t); return __builtin_bit_cast(unsigned, b); }
; __device__ __forceinline__ float sigm(float x) { return frcp(1.f + fexp2(-LOG2E * x)); }
;   __device__ __forceinline__ void operator()(const pg8::f32x4 (&acc)[2][2][4][2], const pg8::Unit& u, int wr, int wc, int fr, int fq) const {
;     ...
;       for (int m = 0; m < 4; ++m) {
;         const float r = rs[m]; float v[8];
; #pragma unroll
;         for (int n = 0; n < 2; ++n)
; #pragma unroll
;           for (int c = 0; c < 4; ++c) { const float g = acc[ai][0][m][n][c] * r, uu = acc[ai][1][m][n][c] * r; v[4 * n + c] = g * sigm(g) * uu; }
;         u32x4 w; w.x = pk2(v[0], v[1]); w.y = pk2(v[2], v[3]); w.z = pk2(v[4], v[5]); w.w = pk2(v[6], v[7]);
;         *(u32x4*)(hbuf + (unsigned)(row0 + ai * 128 + m * 16) * DFF + col0) = w;
	v_rcp_f32_e32 v229, v229
	v_rcp_f32_e32 v230, v230
	v_rcp_f32_e32 v231, v231
	v_rcp_f32_e32 v232, v232
	v_rcp_f32_e32 v233, v233
	v_rcp_f32_e32 v234, v234
	v_rcp_f32_e32 v235, v235
	v_pk_mul_f32 v[44:45], v[44:45], v[228:229]
	v_pk_mul_f32 v[46:47], v[46:47], v[230:231]
	v_pk_mul_f32 v[40:41], v[40:41], v[232:233]
	v_pk_mul_f32 v[42:43], v[42:43], v[234:235]
	v_cvt_pk_bf16_f32 v236, v44, v45
	v_cvt_pk_bf16_f32 v237, v46, v47
	v_cvt_pk_bf16_f32 v238, v40, v41
	v_cvt_pk_bf16_f32 v239, v42, v43
	s_nop 0
	global_store_dwordx4 v[242:243], v[236:239], off
	v_lshl_add_u64 v[242:243], v[242:243], 0, s[100:101]
	v_pk_mul_f32 v[228:229], v[28:29], v[200:201] op_sel_hi:[1,0]
	v_pk_mul_f32 v[230:231], v[30:31], v[200:201] op_sel_hi:[1,0]
	v_pk_mul_f32 v[232:233], v[24:25], v[200:201] op_sel_hi:[1,0]
	v_pk_mul_f32 v[234:235], v[26:27], v[200:201] op_sel_hi:[1,0]
	v_exp_f32_e32 v228, v228
	v_exp_f32_e32 v229, v229
	v_exp_f32_e32 v230, v230
	v_exp_f32_e32 v231, v231
	v_exp_f32_e32 v232, v232
	v_exp_f32_e32 v233, v233
	v_exp_f32_e32 v234, v234
	v_exp_f32_e32 v235, v235
	v_pk_mul_f32 v[28:29], v[28:29], v[20:21]
	v_pk_mul_f32 v[30:31], v[30:31], v[22:23]
	v_pk_mul_f32 v[24:25], v[24:25], v[16:17]
	v_pk_mul_f32 v[26:27], v[26:27], v[18:19]
	v_pk_fma_f32 v[228:229], v[228:229], v[184:185], v[184:185] op_sel_hi:[1,0,0]
	v_pk_fma_f32 v[230:231], v[230:231], v[184:185], v[184:185] op_sel_hi:[1,0,0]
	v_pk_fma_f32 v[232:233], v[232:233], v[184:185], v[184:185] op_sel_hi:[1,0,0]
	v_pk_fma_f32 v[234:235], v[234:235], v[184:185], v[184:185] op_sel_hi:[1,0,0]
	v_rcp_f32_e32 v228, v228
	v_rcp_f32_e32 v229, v229
	v_rcp_f32_e32 v230, v230
	v_rcp_f32_e32 v231, v231
	v_rcp_f32_e32 v232, v232
	v_rcp_f32_e32 v233, v233
	v_rcp_f32_e32 v234, v234
	v_rcp_f32_e32 v235, v235
	v_pk_mul_f32 v[28:29], v[28:29], v[228:229]
	v_pk_mul_f32 v[30:31], v[30:31], v[230:231]
	v_pk_mul_f32 v[24:25], v[24:25], v[232:233]
	v_pk_mul_f32 v[26:27], v[26:27], v[234:235]
	v_cvt_pk_bf16_f32 v236, v28, v29
	v_cvt_pk_bf16_f32 v237, v30, v31
	v_cvt_pk_bf16_f32 v238, v24, v25
	v_cvt_pk_bf16_f32 v239, v26, v27
	s_nop 0
	global_store_dwordx4 v[242:243], v[236:239], off
	v_lshl_add_u64 v[242:243], v[242:243], 0, s[100:101]
	v_pk_mul_f32 v[228:229], v[12:13], v[202:203] op_sel_hi:[1,0]
	v_pk_mul_f32 v[230:231], v[14:15], v[202:203] op_sel_hi:[1,0]
	v_pk_mul_f32 v[232:233], v[8:9], v[202:203] op_sel_hi:[1,0]
	v_pk_mul_f32 v[234:235], v[10:11], v[202:203] op_sel_hi:[1,0]
	v_exp_f32_e32 v228, v228
	v_exp_f32_e32 v229, v229
	v_exp_f32_e32 v230, v230
	v_exp_f32_e32 v231, v231
	v_exp_f32_e32 v232, v232
	v_exp_f32_e32 v233, v233
	v_exp_f32_e32 v234, v234
	v_exp_f32_e32 v235, v235
	v_pk_mul_f32 v[12:13], v[12:13], v[4:5]
	v_pk_mul_f32 v[14:15], v[14:15], v[6:7]
	v_pk_mul_f32 v[8:9], v[8:9], v[0:1]
	v_pk_mul_f32 v[10:11], v[10:11], v[2:3]
	v_pk_fma_f32 v[228:229], v[228:229], v[186:187], v[186:187] op_sel_hi:[1,0,0]
	v_pk_fma_f32 v[230:231], v[230:231], v[186:187], v[186:187] op_sel_hi:[1,0,0]
	v_pk_fma_f32 v[232:233], v[232:233], v[186:187], v[186:187] op_sel_hi:[1,0,0]
	v_pk_fma_f32 v[234:235], v[234:235], v[186:187], v[186:187] op_sel_hi:[1,0,0]
	v_rcp_f32_e32 v228, v228
	v_rcp_f32_e32 v229, v229
	v_rcp_f32_e32 v230, v230
	v_rcp_f32_e32 v231, v231
	v_rcp_f32_e32 v232, v232
	v_rcp_f32_e32 v233, v233
	v_rcp_f32_e32 v234, v234
	v_rcp_f32_e32 v235, v235
	v_pk_mul_f32 v[12:13], v[12:13], v[228:229]
	v_pk_mul_f32 v[14:15], v[14:15], v[230:231]
	v_pk_mul_f32 v[8:9], v[8:9], v[232:233]
	v_pk_mul_f32 v[10:11], v[10:11], v[234:235]
	v_cvt_pk_bf16_f32 v236, v12, v13
	v_cvt_pk_bf16_f32 v237, v14, v15
	v_cvt_pk_bf16_f32 v238, v8, v9
	v_cvt_pk_bf16_f32 v239, v10, v11
	s_nop 0
	global_store_dwordx4 v[242:243], v[236:239], off
	s_andn2_b64 vcc, exec, s[4:5]
	s_mov_b64 s[4:5], -1
	s_cbranch_vccnz .LBB0_1603
	s_andn2_b64 vcc, exec, s[12:13]
	s_cbranch_vccnz .LBB0_1602
	s_barrier
	s_branch .LBB0_1602

; __global__ void __launch_bounds__(512, 2) mega_fwd(Params p_arg) {
	.amdhsa_kernel _Z8mega_fwd6Params
		.amdhsa_group_segment_fixed_size 147472
		.amdhsa_private_segment_fixed_size 0
		.amdhsa_kernarg_size 528
		.amdhsa_user_sgpr_count 2
		.amdhsa_user_sgpr_dispatch_ptr 0
		.amdhsa_user_sgpr_queue_ptr 0
		.amdhsa_user_sgpr_kernarg_segment_ptr 1
		.amdhsa_user_sgpr_dispatch_id 0
		.amdhsa_user_sgpr_kernarg_preload_length 0
		.amdhsa_user_sgpr_kernarg_preload_offset 0
		.amdhsa_user_sgpr_private_segment_size 0
		.amdhsa_uses_dynamic_stack 0
		.amdhsa_enable_private_segment 0
		.amdhsa_system_sgpr_workgroup_id_x 1
		.amdhsa_system_sgpr_workgroup_id_y 0
		.amdhsa_system_sgpr_workgroup_id_z 0
		.amdhsa_system_sgpr_workgroup_info 0
		.amdhsa_system_vgpr_workitem_id 2
		.amdhsa_next_free_vgpr 256
		.amdhsa_next_free_sgpr 102
		.amdhsa_accum_offset 256
		.amdhsa_reserve_vcc 1
		.amdhsa_float_round_mode_32 0
		.amdhsa_float_round_mode_16_64 0
		.amdhsa_float_denorm_mode_32 3
		.amdhsa_float_denorm_mode_16_64 3
		.amdhsa_dx10_clamp 1
		.amdhsa_ieee_mode 1
		.amdhsa_fp16_overflow 0
		.amdhsa_tg_split 0
		.amdhsa_exception_fp_ieee_invalid_op 0
		.amdhsa_exception_fp_denorm_src 0
		.amdhsa_exception_fp_ieee_div_zero 0
		.amdhsa_exception_fp_ieee_overflow 0
		.amdhsa_exception_fp_ieee_underflow 0
		.amdhsa_exception_fp_ieee_inexact 0
		.amdhsa_exception_int_div_zero 0
	.end_amdhsa_kernel

; __global__ void __launch_bounds__(512, 2) mega_fwd(Params p_arg) {
amdhsa.kernels:
  - .agpr_count:     0
    .args:
      - .offset:         0
        .size:           272
        .value_kind:     by_value
      - .offset:         272
        .size:           4
        .value_kind:     hidden_block_count_x
      - .offset:         276
        .size:           4
        .value_kind:     hidden_block_count_y
      - .offset:         280
        .size:           4
        .value_kind:     hidden_block_count_z
      - .offset:         284
        .size:           2
        .value_kind:     hidden_group_size_x
      - .offset:         286
        .size:           2
        .value_kind:     hidden_group_size_y
      - .offset:         288
        .size:           2
        .value_kind:     hidden_group_size_z
      - .offset:         290
        .size:           2
        .value_kind:     hidden_remainder_x
      - .offset:         292
        .size:           2
        .value_kind:     hidden_remainder_y
      - .offset:         294
        .size:           2
        .value_kind:     hidden_remainder_z
      - .offset:         312
        .size:           8
        .value_kind:     hidden_global_offset_x
      - .offset:         320
        .size:           8
        .value_kind:     hidden_global_offset_y
      - .offset:         328
        .size:           8
        .value_kind:     hidden_global_offset_z
      - .offset:         336
        .size:           2
        .value_kind:     hidden_grid_dims
      - .offset:         360
        .size:           8
        .value_kind:     hidden_multigrid_sync_arg
    .group_segment_fixed_size: 147472
    .kernarg_segment_align: 8
    .kernarg_segment_size: 528
    .language:       OpenCL C
    .language_version:
      - 2
      - 0
    .max_flat_workgroup_size: 512
    .name:           _Z8mega_fwd6Params
    .private_segment_fixed_size: 0
    .sgpr_count:     108
    .sgpr_spill_count: 35
    .symbol:         _Z8mega_fwd6Params.kd
    .uniform_work_group_size: 1
    .uses_dynamic_stack: false
    .vgpr_count:     256
    .vgpr_spill_count: 0
    .wavefront_size: 64
